# P6: tile 0 through the main tile loop on WG 128; S5 pass-2 scan in registers (transposed Bu MFMA + permlane32_swap); C.s+gelu block with reads up front and interleaved chains
# speedup vs baseline: 1.0133x; 1.0050x over previous
; #define LAS __attribute__((address_space(3)))
;     __device__ __forceinline__ const float* in(int i) const { return karg_in(i); }
; #define FTID const int ftid_ = fresh_tid()
; #define WAVE (__builtin_amdgcn_readfirstlane(ftid_ >> 6))
; template <bool PASS2>
; __device__ __forceinline__ void s5_tile(const Ctx& C, int T, int sb_lo, int sb_hi, LAS unsigned char* lds, int wave, int lane) {
;     const bool sample = (T == NTILE - 1);
;     const int r0 = T * 128;
;     LAS bf16* XU = (LAS bf16*)(lds + wave * S5W_BYTES);
;     LAS bf16* BH = XU + 32 * XU_STRIDE;
;     const int tl = lane & 31, hh = lane >> 5, fr = lane & 15, kq = lane >> 4, xrow = lane >> 3, xpart = lane & 7;
;     const float* LAM = C.LAM();
;     const bf16* Zb = C.Z() + (size_t)1024 + 64 * wave;
;     float sr[4], si[4], lr[4], li[4], dsk[4];
; #pragma unroll
;     for (int gi = 0; gi < 4; ++gi) { const int g = wave * 4 + gi; sr[gi] = 0.f; si[gi] = 0.f; lr[gi] = LAM[0 * 2048 + g * 64 + lane]; li[gi] = LAM[1 * 2048 + g * 64 + lane];
;         dsk[gi] = PASS2 ? C.in(21)[16 * g + fr] : 0.f; }
; __global__ void __launch_bounds__(NTHREADS, 2) fwd_kernel(Args args) {
;     ...
;     { FTID; const bool swap0 = GSZ > 128;
;       for (int T = BX; T < NTILE - 1; T += GSZ) { if (swap0 && T == 0) continue; s5_tile<true>(C, T, 0, 4, lds, WAVE, LANE); }
.LBB0_656:
	s_or_b64 exec, exec, s[8:9]
	v_mov_b32_e32 v160, v182
	s_cmpk_gt_i32 s94, 0x80
	s_waitcnt lgkmcnt(0)
	v_cndmask_b32_e64 v0, 0, 1, s[10:11]
	s_barrier
	s_cselect_b64 s[52:53], -1, 0
	v_cmp_ne_u32_e64 s[8:9], 1, v0
	s_andn2_b64 vcc, exec, s[10:11]
	v_bfe_u32 v162, v160, 3, 3
	v_bfe_u32 v161, v160, 4, 2
	v_and_b32_e32 v96, 48, v160
	s_cbranch_vccnz .LBB0_673
	v_and_b32_e32 v98, 63, v160
	v_and_b32_e32 v97, 31, v160
	v_and_b32_e32 v99, 15, v160
	v_bfe_u32 v1, v160, 5, 1
	v_and_b32_e32 v2, 7, v160
	v_lshlrev_b32_e32 v0, 3, v161
	v_or_b32_e32 v103, 0x800, v98
	v_or_b32_e32 v105, 0x1000, v98
	v_or_b32_e32 v163, 0x1800, v98
	v_mov_b32_e32 v101, 0
	v_lshlrev_b32_e32 v102, 3, v2
	v_lshlrev_b32_e32 v104, 3, v1
	v_lshlrev_b32_e32 v164, 4, v2
	v_mul_u32_u24_e32 v165, 0x90, v97
	v_lshlrev_b32_e32 v166, 4, v1
	v_mul_u32_u24_e32 v167, 0x110, v97
	v_lshlrev_b32_e32 v168, 2, v98
	v_mul_u32_u24_e32 v169, 0x90, v162
	v_mul_u32_u24_e32 v170, 0x240, v161
	v_mul_u32_u24_e32 v171, 0x110, v99
	v_lshl_or_b32 v172, s33, 7, v162
	s_lshl_b32 s42, s94, 7
	s_mov_b32 s55, 0
	s_mov_b64 s[56:57], 0x2b00000
	s_mov_b64 s[58:59], 0xb200800
	s_movk_i32 s43, 0xc00
	s_mov_b64 s[60:61], 0x2a00000
	v_lshlrev_b32_e32 v106, 1, v0
	s_mov_b32 s47, 0x11300000
	s_mov_b32 s74, 0x8080000
	s_mov_b32 s75, 0x8084000
	s_mov_b32 s76, s33
	s_mov_b32 s98, 0
	s_mov_b32 s77, s33
	s_branch .LBB0_659

;     __device__ __forceinline__ const float* in(int i) const { return karg_in(i); }
; template <bool PASS2>
; __device__ __forceinline__ void s5_tile(const Ctx& C, int T, int sb_lo, int sb_hi, LAS unsigned char* lds, int wave, int lane) {
;     ...
;     const float* LAM = C.LAM();
;     const bf16* Zb = C.Z() + (size_t)1024 + 64 * wave;
;     float sr[4], si[4], lr[4], li[4], dsk[4];
; #pragma unroll
;     for (int gi = 0; gi < 4; ++gi) { const int g = wave * 4 + gi; sr[gi] = 0.f; si[gi] = 0.f; lr[gi] = LAM[0 * 2048 + g * 64 + lane]; li[gi] = LAM[1 * 2048 + g * 64 + lane];
;         dsk[gi] = PASS2 ? C.in(21)[16 * g + fr] : 0.f; }
;     if (PASS2 && !sample) {
;         const int k = T & 127, tb = T - k;
;         float l8r[4], l8i[4];
; #pragma unroll
;         for (int gi = 0; gi < 4; ++gi) { l8r[gi] = LAM[2 * 2048 + (wave * 4 + gi) * 64 + lane]; l8i[gi] = LAM[3 * 2048 + (wave * 4 + gi) * 64 + lane]; }
;         const v2f* Ep = (const v2f*)C.E() + ((size_t)tb * NG + wave * 4) * NP + lane;
.Lmy_p6_tile_entry:
	s_mov_b64 s[0:1], s[80:81]
	s_load_dwordx2 s[10:11], s[0:1], 0x110
	v_readfirstlane_b32 s3, v160
	s_ashr_i32 s67, s3, 6
	s_mov_b64 s[0:1], s[80:81]
	s_mov_b64 s[12:13], s[80:81]
	s_waitcnt lgkmcnt(0)
	s_add_u32 s10, s10, 0x2a40000
	s_addc_u32 s11, s11, 0
	s_lshl_b32 s14, s67, 8
	v_or_b32_e32 v0, s14, v98
	v_ashrrev_i32_e32 v1, 31, v0
	v_add_u32_e32 v2, s14, v103
	v_lshl_add_u64 v[0:1], v[0:1], 2, s[10:11]
	v_ashrrev_i32_e32 v3, 31, v2
	v_lshl_add_u64 v[2:3], v[2:3], 2, s[10:11]
	global_load_dword v173, v[0:1], off
	global_load_dword v174, v[2:3], off
	s_load_dwordx2 s[12:13], s[12:13], 0xa8
	s_and_b32 s72, s3, 0xffffffc0
	s_lshl_b32 s62, s67, 2
	v_or_b32_e32 v6, s72, v99
	v_ashrrev_i32_e32 v7, 31, v6
	s_or_b32 s64, s62, 1
	s_waitcnt lgkmcnt(0)
	v_lshl_add_u64 v[0:1], v[6:7], 2, s[12:13]
	s_lshl_b32 s3, s64, 6
	global_load_dword v175, v[0:1], off
	v_or_b32_e32 v0, s3, v98
	v_ashrrev_i32_e32 v1, 31, v0
	v_add_u32_e32 v2, s3, v103
	v_lshl_add_u64 v[0:1], v[0:1], 2, s[10:11]
	v_ashrrev_i32_e32 v3, 31, v2
	s_mov_b64 s[12:13], s[80:81]
	v_lshl_add_u64 v[2:3], v[2:3], 2, s[10:11]
	global_load_dword v176, v[0:1], off
	global_load_dword v177, v[2:3], off
	s_load_dwordx2 s[12:13], s[12:13], 0xa8
	v_lshl_or_b32 v4, s64, 4, v99
	v_ashrrev_i32_e32 v5, 31, v4
	s_or_b32 s66, s62, 2
	s_lshl_b32 s3, s66, 6
	s_waitcnt lgkmcnt(0)
	v_lshl_add_u64 v[0:1], v[4:5], 2, s[12:13]
	global_load_dword v178, v[0:1], off
	v_or_b32_e32 v0, s3, v98
	v_ashrrev_i32_e32 v1, 31, v0
	v_add_u32_e32 v2, s3, v103
	v_lshl_add_u64 v[0:1], v[0:1], 2, s[10:11]
	v_ashrrev_i32_e32 v3, 31, v2
	s_mov_b64 s[12:13], s[80:81]
	v_lshl_add_u64 v[2:3], v[2:3], 2, s[10:11]
	global_load_dword v179, v[0:1], off
	global_load_dword v180, v[2:3], off
	s_load_dwordx2 s[12:13], s[12:13], 0xa8
	v_lshl_or_b32 v2, s66, 4, v99
	v_ashrrev_i32_e32 v3, 31, v2
	s_or_b32 s68, s62, 3
	s_lshl_b32 s3, s68, 6
	s_waitcnt lgkmcnt(0)
	v_lshl_add_u64 v[0:1], v[2:3], 2, s[12:13]
	global_load_dword v181, v[0:1], off
	v_or_b32_e32 v0, s3, v98
	v_ashrrev_i32_e32 v1, 31, v0
	v_add_u32_e32 v8, s3, v103
	v_lshl_add_u64 v[0:1], v[0:1], 2, s[10:11]
	v_ashrrev_i32_e32 v9, 31, v8
	s_mov_b64 s[12:13], s[80:81]
	v_lshl_add_u64 v[8:9], v[8:9], 2, s[10:11]
	global_load_dword v189, v[0:1], off
	global_load_dword v190, v[8:9], off
	s_load_dwordx2 s[12:13], s[12:13], 0xa8
	v_lshl_or_b32 v0, s68, 4, v99
	v_ashrrev_i32_e32 v1, 31, v0
	s_or_b32 s3, s14, 64
	v_add_u32_e32 v12, s3, v105
	s_waitcnt lgkmcnt(0)
	v_lshl_add_u64 v[8:9], v[0:1], 2, s[12:13]
	v_add_u32_e32 v14, s3, v163
	s_or_b32 s3, s14, 0x80
	global_load_dword v191, v[8:9], off
	v_add_u32_e32 v8, s14, v105
	v_add_u32_e32 v10, s14, v163
	v_add_u32_e32 v16, s3, v105
	v_add_u32_e32 v18, s3, v163
	s_or_b32 s3, s14, 0xc0
	v_ashrrev_i32_e32 v9, 31, v8
	v_ashrrev_i32_e32 v11, 31, v10
	v_ashrrev_i32_e32 v13, 31, v12
	v_ashrrev_i32_e32 v15, 31, v14
	v_add_u32_e32 v20, s3, v105
	v_add_u32_e32 v22, s3, v163
	v_lshl_add_u64 v[8:9], v[8:9], 2, s[10:11]
	v_lshl_add_u64 v[10:11], v[10:11], 2, s[10:11]
	v_lshl_add_u64 v[12:13], v[12:13], 2, s[10:11]
	v_lshl_add_u64 v[14:15], v[14:15], 2, s[10:11]
	v_ashrrev_i32_e32 v17, 31, v16
	v_ashrrev_i32_e32 v19, 31, v18
	v_ashrrev_i32_e32 v21, 31, v20
	v_ashrrev_i32_e32 v23, 31, v22
	v_lshl_add_u64 v[16:17], v[16:17], 2, s[10:11]
	v_lshl_add_u64 v[18:19], v[18:19], 2, s[10:11]
	v_lshl_add_u64 v[20:21], v[20:21], 2, s[10:11]
	v_lshl_add_u64 v[22:23], v[22:23], 2, s[10:11]
	global_load_dword v8, v[8:9], off
	s_nop 0
	global_load_dword v10, v[10:11], off
	s_nop 0
	global_load_dword v9, v[12:13], off
	global_load_dword v11, v[14:15], off
	s_nop 0
	global_load_dword v12, v[16:17], off
	global_load_dword v14, v[18:19], off
	global_load_dword v13, v[20:21], off
	global_load_dword v15, v[22:23], off
	s_and_b32 s65, s77, 0x7f
	s_ashr_i32 s63, s62, 31
	s_mov_b64 s[10:11], s[80:81]
	s_cmp_eq_u32 s65, 0
	s_cbranch_scc1 .LBB0_664
	s_load_dwordx2 s[10:11], s[10:11], 0x110
	s_and_b32 s12, s77, 0xffffff80
	s_ashr_i32 s13, s12, 31
	s_lshl_b64 s[12:13], s[12:13], 14
	v_lshlrev_b32_e32 v100, 3, v98
	s_waitcnt lgkmcnt(0)
	s_add_u32 s3, s10, s12
	s_addc_u32 s12, s11, s13
	s_lshl_b64 s[10:11], s[62:63], 9
	s_add_u32 s10, s3, s10
	s_addc_u32 s11, s12, s11
	s_and_b32 s3, s76, 0x7f
	v_lshl_add_u64 v[16:17], s[10:11], 0, v[100:101]
	s_add_i32 s10, s3, 15
	s_lshr_b32 s69, s10, 4
	s_and_b32 s10, s10, 0xf0
	v_mov_b32_e32 v114, 0
	v_lshl_add_u64 v[16:17], v[16:17], 0, s[56:57]
	s_sub_i32 s73, s3, s10
	v_mov_b32_e32 v115, v114
	v_mov_b32_e32 v110, v114
	v_mov_b32_e32 v111, v114
	v_mov_b32_e32 v112, v114
	v_mov_b32_e32 v113, v114
	v_mov_b32_e32 v108, v114
	v_mov_b32_e32 v109, v114

; template <bool PASS2>
; __device__ __forceinline__ void s5_tile(const Ctx& C, int T, int sb_lo, int sb_hi, LAS unsigned char* lds, int wave, int lane) {
;     ...
;     v4u xn[4];
;     {
;         const int sb0 = sb_lo;
; #pragma unroll
;         for (int i = 0; i < 4; ++i) xn[i] = *(const v4u*)(Zb + (size_t)(r0 + 32 * sb0 + xrow + 8 * i) * DIN + 8 * xpart);
;     }
;     const bf16* BBt = C.BB(); const bf16* CMt = C.CM();
;     bfx8 bbn[4], cmn[4];
; #pragma unroll
;     for (int cb = 0; cb < 4; ++cb) bbn[cb] = *(const bfx8*)(BBt + ((size_t)(wave * 4 * 128 + cb * 32 + tl)) * GN + 8 * hh);
;     if (PASS2) {
; #pragma unroll
;         for (int ks = 0; ks < 4; ++ks) cmn[ks] = *(const bfx8*)(CMt + ((size_t)(wave * 4 * GN + fr)) * 128 + 32 * ks + 8 * kq);
;     }
;     for (int sb = sb_lo; sb < sb_hi; ++sb) {
.LBB0_665:
	s_load_dwordx2 s[12:13], s[0:1], 0x110
	s_mul_i32 s0, s67, 0x3400
	s_ashr_i32 s73, s72, 31
	s_add_i32 s3, s0, 0
	s_lshl_b64 s[10:11], s[72:73], 1
	s_waitcnt lgkmcnt(0)
	s_add_u32 s0, s12, s10
	s_addc_u32 s1, s13, s11
	v_lshlrev_b32_e32 v100, 1, v102
	s_waitcnt vmcnt(3)
	v_lshl_or_b32 v12, s77, 7, v162
	v_lshl_add_u64 v[8:9], s[0:1], 0, v[100:101]
	v_lshl_add_u64 v[116:117], v[8:9], 0, s[58:59]
	v_or_b32_e32 v10, 8, v12
	v_mad_i64_i32 v[8:9], s[0:1], v12, s43, v[116:117]
	v_mad_i64_i32 v[10:11], s[0:1], v10, s43, v[116:117]
	global_load_dwordx4 v[16:19], v[8:9], off
	global_load_dwordx4 v[20:23], v[10:11], off
	v_or_b32_e32 v8, 16, v12
	v_or_b32_e32 v10, 24, v12
	v_mad_i64_i32 v[8:9], s[0:1], v8, s43, v[116:117]
	v_mad_i64_i32 v[10:11], s[0:1], v10, s43, v[116:117]
	s_mov_b64 s[0:1], s[80:81]
	global_load_dwordx4 v[24:27], v[8:9], off
	global_load_dwordx4 v[28:31], v[10:11], off
	s_mov_b64 s[12:13], s[80:81]
	s_load_dwordx2 s[0:1], s[0:1], 0x110
	s_load_dwordx2 s[12:13], s[12:13], 0x110
	v_lshlrev_b32_e32 v8, 1, v104
	v_mov_b32_e32 v9, v101
	s_waitcnt lgkmcnt(0)
	v_lshl_add_u64 v[8:9], s[0:1], 0, v[8:9]
	v_lshlrev_b64 v[6:7], 8, v[6:7]
	s_add_u32 s0, s12, 0x2a20000
	s_addc_u32 s1, s13, 0
	v_lshl_add_u64 v[10:11], s[0:1], 0, v[6:7]
	v_mov_b32_e32 v107, v101
	v_lshl_add_u64 v[10:11], v[10:11], 0, v[106:107]
	global_load_dwordx4 v[32:35], v[10:11], off offset:192
	global_load_dwordx4 v[36:39], v[10:11], off offset:128
	global_load_dwordx4 v[40:43], v[10:11], off offset:64
	global_load_dwordx4 v[44:47], v[10:11], off
	v_lshlrev_b32_e32 v231, 1, v97
	v_lshl_or_b32 v10, s67, 9, v231
	v_or_b32_e32 v12, 0x41, v10
	s_waitcnt vmcnt(9)
	v_ashrrev_i32_e32 v13, 31, v12
	v_lshl_add_u64 v[8:9], v[8:9], 0, s[60:61]
	v_lshlrev_b64 v[12:13], 5, v[12:13]
	v_lshl_add_u64 v[118:119], v[8:9], 0, v[12:13]
	v_or_b32_e32 v12, 0x40, v10
	v_ashrrev_i32_e32 v13, 31, v12
	v_lshlrev_b64 v[12:13], 5, v[12:13]
	v_lshl_add_u64 v[120:121], v[8:9], 0, v[12:13]
	v_or_b32_e32 v12, 0x1, v10
	v_ashrrev_i32_e32 v13, 31, v12
	v_lshlrev_b64 v[12:13], 5, v[12:13]
	v_ashrrev_i32_e32 v11, 31, v10
	v_lshl_add_u64 v[122:123], v[8:9], 0, v[12:13]
	v_lshlrev_b64 v[10:11], 5, v[10:11]
	global_load_dwordx4 v[64:67], v[118:119], off
	global_load_dwordx4 v[68:71], v[120:121], off
	v_lshl_add_u64 v[124:125], v[8:9], 0, v[10:11]
	global_load_dwordx4 v[72:75], v[122:123], off
	global_load_dwordx4 v[76:79], v[124:125], off
	v_lshl_or_b32 v12, s64, 7, v231
	v_ashrrev_i32_e32 v13, 31, v12
	s_waitcnt vmcnt(12)
	v_lshlrev_b64 v[14:15], 5, v[12:13]
	v_lshl_add_u64 v[126:127], v[8:9], 0, v[14:15]
	v_or_b32_e32 v14, 0x1, v12
	v_ashrrev_i32_e32 v15, 31, v14
	v_lshlrev_b64 v[14:15], 5, v[14:15]
	v_lshl_add_u64 v[10:11], s[0:1], 0, v[106:107]
	v_lshl_add_u64 v[128:129], v[8:9], 0, v[14:15]
	v_or_b32_e32 v14, 0x40, v12
	v_or_b32_e32 v12, 0x41, v12
	v_lshlrev_b64 v[4:5], 8, v[4:5]
	v_ashrrev_i32_e32 v13, 31, v12
	v_lshl_add_u64 v[134:135], v[10:11], 0, v[4:5]
	v_lshl_or_b32 v4, s66, 7, v231
	v_lshlrev_b64 v[12:13], 5, v[12:13]
	v_ashrrev_i32_e32 v5, 31, v4
	v_lshl_add_u64 v[132:133], v[8:9], 0, v[12:13]
	v_lshlrev_b64 v[12:13], 5, v[4:5]
	v_lshl_add_u64 v[136:137], v[8:9], 0, v[12:13]
	v_or_b32_e32 v12, 0x1, v4
	v_ashrrev_i32_e32 v13, 31, v12
	v_lshlrev_b64 v[12:13], 5, v[12:13]
	v_lshl_add_u64 v[138:139], v[8:9], 0, v[12:13]
	v_or_b32_e32 v12, 0x40, v4
	v_or_b32_e32 v4, 0x41, v4
	v_lshlrev_b64 v[2:3], 8, v[2:3]
	v_ashrrev_i32_e32 v5, 31, v4
	v_lshl_add_u64 v[144:145], v[10:11], 0, v[2:3]
	v_lshl_or_b32 v2, s68, 7, v231
	v_lshlrev_b64 v[4:5], 5, v[4:5]
	v_ashrrev_i32_e32 v3, 31, v2
	v_lshl_add_u64 v[142:143], v[8:9], 0, v[4:5]
	v_lshlrev_b64 v[4:5], 5, v[2:3]
	v_lshl_add_u64 v[146:147], v[8:9], 0, v[4:5]
	v_or_b32_e32 v4, 0x1, v2
	v_ashrrev_i32_e32 v5, 31, v4
	v_lshlrev_b64 v[4:5], 5, v[4:5]
	v_lshl_add_u64 v[148:149], v[8:9], 0, v[4:5]
	v_or_b32_e32 v4, 0x40, v2
	v_or_b32_e32 v2, 0x41, v2
	v_ashrrev_i32_e32 v15, 31, v14
	v_ashrrev_i32_e32 v13, 31, v12
	v_ashrrev_i32_e32 v5, 31, v4
	v_ashrrev_i32_e32 v3, 31, v2
	v_add_u32_e32 v48, s3, v164
	v_lshl_add_u32 v49, v99, 1, s3
	v_add_u32_e32 v50, s3, v165
	v_add_u32_e32 v51, s3, v167
	v_add_u32_e32 v52, s3, v96
	v_lshlrev_b64 v[14:15], 5, v[14:15]
	v_lshlrev_b64 v[12:13], 5, v[12:13]
	v_lshlrev_b64 v[4:5], 5, v[4:5]
	v_lshlrev_b64 v[2:3], 5, v[2:3]
	v_lshlrev_b64 v[0:1], 8, v[0:1]
	v_add_u32_e32 v107, s3, v168
	v_lshl_add_u64 v[130:131], v[8:9], 0, v[14:15]
	v_lshl_add_u64 v[140:141], v[8:9], 0, v[12:13]
	v_lshl_add_u64 v[150:151], v[8:9], 0, v[4:5]
	v_lshl_add_u64 v[152:153], v[8:9], 0, v[2:3]
	v_lshl_add_u64 v[154:155], v[10:11], 0, v[0:1]
	v_lshl_add_u64 v[156:157], v[10:11], 0, v[6:7]
	s_mov_b32 s14, 0
	v_add_u32_e32 v192, v50, v166
	v_add_u32_e32 v193, v51, v104
	v_add_u32_e32 v194, v52, v171
	v_add_u32_e32 v195, v49, v170
	v_add_u32_e32 v196, v48, v169
	s_mov_b32 s15, 0
	s_branch .LBB0_667
; #define LAS __attribute__((address_space(3)))
; template <bool PASS2>
; __device__ __forceinline__ void s5_tile(const Ctx& C, int T, int sb_lo, int sb_hi, LAS unsigned char* lds, int wave, int lane) {
;     ...
;         for (int gi = 0; gi < 4; ++gi) {
;             const int g = wave * 4 + gi, gnx = wave * 4 + ((gi + 1) & 3);
;             bfx8 bb[4], cm[4];
; #pragma unroll
;             for (int cb = 0; cb < 4; ++cb) { bb[cb] = bbn[cb]; bbn[cb] = *(const bfx8*)(BBt + ((size_t)(gnx * 128 + cb * 32 + tl)) * GN + 8 * hh); }
;             if (PASS2) {
; #pragma unroll
;                 for (int ks = 0; ks < 4; ++ks) { cm[ks] = cmn[ks]; cmn[ks] = *(const bfx8*)(CMt + ((size_t)(gnx * GN + fr)) * 128 + 32 * ks + 8 * kq); }
;             }
;             float s0ar = 0.f, s0ai = 0.f, s0br = 0.f, s0bi = 0.f;
;             if (sample) { const size_t o0 = ((size_t)(2 * sb) * NG + g) * NP + lane, o1 = o0 + (size_t)NG * NP;
;                 s0ar = C.in(2)[o0]; s0ai = C.in(3)[o0]; s0br = C.in(2)[o1]; s0bi = C.in(3)[o1]; }
;             const bfx8 a = *(const LAS bfx8*)(XU + tl * XU_STRIDE + 16 * gi + 8 * hh);
; #pragma unroll
;             for (int cb = 0; cb < 4; ++cb) {
;                 v16f acc;
; #pragma unroll
;                 for (int r = 0; r < 16; ++r) acc[r] = 0.f;
;                 acc = __builtin_amdgcn_mfma_f32_32x32x16_bf16(bb[cb], a, acc, 0, 0, 0);
; #pragma unroll
;                 for (int rg = 0; rg < 4; ++rg) { v2u w; w.x = cvt_pk_c(acc[4 * rg], acc[4 * rg + 1]); w.y = cvt_pk_c(acc[4 * rg + 2], acc[4 * rg + 3]);
;                     *(LAS v2u*)(BH + tl * BH_STRIDE + cb * 32 + 8 * rg + 4 * hh) = w; }
;             }
;             LDS_FENCE();
;             {
;                 unsigned bu[32];
; #pragma unroll
;                 for (int t = 0; t < 32; ++t) bu[t] = *(const LAS unsigned*)(BH + t * BH_STRIDE + 2 * lane);
;                 LDS_FENCE();
;                 float xr = sr[gi], xi = si[gi];
; #pragma unroll
;                 for (int t = 0; t < 32; ++t) {
;                     if (sample && t == 0) { xr = s0ar; xi = s0ai; }
;                     if (sample && t == 16) { xr = s0br; xi = s0bi; }
;                     const float nr = fmaf(lr[gi], xr, fmaf(-li[gi], xi, bf_lo(bu[t]))), ni = fmaf(lr[gi], xi, fmaf(li[gi], xr, bf_hi(bu[t])));
;                     xr = nr; xi = ni;
;                     if (PASS2) {
.LBB0_666:
	s_waitcnt lgkmcnt(0)
	global_load_dwordx4 v[92:95], v[126:127], off
	global_load_dwordx4 v[88:91], v[128:129], off
	global_load_dwordx4 v[84:87], v[130:131], off
	global_load_dwordx4 v[80:83], v[132:133], off
	ds_read_b128 v[250:253], v192
	global_load_dwordx4 v[60:63], v[134:135], off
	global_load_dwordx4 v[56:59], v[134:135], off offset:64
	global_load_dwordx4 v[48:51], v[134:135], off offset:128
	global_load_dwordx4 v[52:55], v[134:135], off offset:192
	s_waitcnt vmcnt(8) lgkmcnt(0)
	v_mfma_f32_32x32x16_bf16 v[0:15], v[250:253], v[76:79], 0
	v_mfma_f32_32x32x16_bf16 v[214:229], v[250:253], v[72:75], 0
	s_mov_b64 s[0:1], s[80:81]
	s_add_i32 s14, s14, 32
	s_add_i32 s15, s15, 1
	s_cmpk_eq_i32 s14, 0x80
	v_mfma_f32_32x32x16_bf16 v[234:249], v[250:253], v[68:71], 0
	v_mfma_f32_32x32x16_bf16 v[198:213], v[250:253], v[64:67], 0
	s_nop 11
	v_permlane32_swap_b32_e32 v0, v234
	v_permlane32_swap_b32_e32 v1, v235
	v_permlane32_swap_b32_e32 v2, v236
	v_permlane32_swap_b32_e32 v3, v237
	v_permlane32_swap_b32_e32 v4, v238
	v_permlane32_swap_b32_e32 v5, v239
	v_permlane32_swap_b32_e32 v6, v240
	v_permlane32_swap_b32_e32 v7, v241
	v_permlane32_swap_b32_e32 v8, v242
	v_permlane32_swap_b32_e32 v9, v243
	v_permlane32_swap_b32_e32 v10, v244
	v_permlane32_swap_b32_e32 v11, v245
	v_permlane32_swap_b32_e32 v12, v246
	v_permlane32_swap_b32_e32 v13, v247
	v_permlane32_swap_b32_e32 v14, v248
	v_permlane32_swap_b32_e32 v15, v249
	v_permlane32_swap_b32_e32 v214, v198
	v_permlane32_swap_b32_e32 v215, v199
	v_permlane32_swap_b32_e32 v216, v200
	v_permlane32_swap_b32_e32 v217, v201
	v_permlane32_swap_b32_e32 v218, v202
	v_permlane32_swap_b32_e32 v219, v203
	v_permlane32_swap_b32_e32 v220, v204
	v_permlane32_swap_b32_e32 v221, v205
	v_permlane32_swap_b32_e32 v222, v206
	v_permlane32_swap_b32_e32 v223, v207
	v_permlane32_swap_b32_e32 v224, v208
	v_permlane32_swap_b32_e32 v225, v209
	v_permlane32_swap_b32_e32 v226, v210
	v_permlane32_swap_b32_e32 v227, v211
	v_permlane32_swap_b32_e32 v228, v212
	v_permlane32_swap_b32_e32 v229, v213
	v_fma_f32 v0, -v174, v112, v0
	v_fma_f32 v214, v174, v114, v214
	v_fma_f32 v114, v173, v114, v0
	v_fma_f32 v112, v173, v112, v214
	v_cvt_pk_bf16_f32 v197, v114, v112
	ds_write_b32 v107, v197 offset:4608
	v_fma_f32 v1, -v174, v112, v1
	v_fma_f32 v215, v174, v114, v215
	v_fma_f32 v114, v173, v114, v1
	v_fma_f32 v112, v173, v112, v215
	v_cvt_pk_bf16_f32 v197, v114, v112
	ds_write_b32 v107, v197 offset:4880
	v_fma_f32 v2, -v174, v112, v2
	v_fma_f32 v216, v174, v114, v216
	v_fma_f32 v114, v173, v114, v2
	v_fma_f32 v112, v173, v112, v216
	v_cvt_pk_bf16_f32 v197, v114, v112
	ds_write_b32 v107, v197 offset:5152
	v_fma_f32 v3, -v174, v112, v3
	v_fma_f32 v217, v174, v114, v217
	v_fma_f32 v114, v173, v114, v3
	v_fma_f32 v112, v173, v112, v217
	v_cvt_pk_bf16_f32 v197, v114, v112
	ds_write_b32 v107, v197 offset:5424
	v_fma_f32 v234, -v174, v112, v234
	v_fma_f32 v198, v174, v114, v198
	v_fma_f32 v114, v173, v114, v234
	v_fma_f32 v112, v173, v112, v198
	v_cvt_pk_bf16_f32 v197, v114, v112
	ds_write_b32 v107, v197 offset:5696
	v_fma_f32 v235, -v174, v112, v235
	v_fma_f32 v199, v174, v114, v199
	v_fma_f32 v114, v173, v114, v235
	v_fma_f32 v112, v173, v112, v199
	v_cvt_pk_bf16_f32 v197, v114, v112
	ds_write_b32 v107, v197 offset:5968
	v_fma_f32 v236, -v174, v112, v236
	v_fma_f32 v200, v174, v114, v200
	v_fma_f32 v114, v173, v114, v236
	v_fma_f32 v112, v173, v112, v200
	v_cvt_pk_bf16_f32 v197, v114, v112
	ds_write_b32 v107, v197 offset:6240
	v_fma_f32 v237, -v174, v112, v237
	v_fma_f32 v201, v174, v114, v201
	v_fma_f32 v114, v173, v114, v237
	v_fma_f32 v112, v173, v112, v201
	v_cvt_pk_bf16_f32 v197, v114, v112
	ds_write_b32 v107, v197 offset:6512
	v_fma_f32 v4, -v174, v112, v4
	v_fma_f32 v218, v174, v114, v218
	v_fma_f32 v114, v173, v114, v4
	v_fma_f32 v112, v173, v112, v218
	v_cvt_pk_bf16_f32 v197, v114, v112
	ds_write_b32 v107, v197 offset:6784
	v_fma_f32 v5, -v174, v112, v5
	v_fma_f32 v219, v174, v114, v219
	v_fma_f32 v114, v173, v114, v5
	v_fma_f32 v112, v173, v112, v219
	v_cvt_pk_bf16_f32 v197, v114, v112
	ds_write_b32 v107, v197 offset:7056
	v_fma_f32 v6, -v174, v112, v6
	v_fma_f32 v220, v174, v114, v220
	v_fma_f32 v114, v173, v114, v6
	v_fma_f32 v112, v173, v112, v220
	v_cvt_pk_bf16_f32 v197, v114, v112
	ds_write_b32 v107, v197 offset:7328
	v_fma_f32 v7, -v174, v112, v7
	v_fma_f32 v221, v174, v114, v221
	v_fma_f32 v114, v173, v114, v7
	v_fma_f32 v112, v173, v112, v221
	v_cvt_pk_bf16_f32 v197, v114, v112
	ds_write_b32 v107, v197 offset:7600
	v_fma_f32 v238, -v174, v112, v238
	v_fma_f32 v202, v174, v114, v202
	v_fma_f32 v114, v173, v114, v238
	v_fma_f32 v112, v173, v112, v202
	v_cvt_pk_bf16_f32 v197, v114, v112
	ds_write_b32 v107, v197 offset:7872
	v_fma_f32 v239, -v174, v112, v239
	v_fma_f32 v203, v174, v114, v203
	v_fma_f32 v114, v173, v114, v239
	v_fma_f32 v112, v173, v112, v203
	v_cvt_pk_bf16_f32 v197, v114, v112
	ds_write_b32 v107, v197 offset:8144
	v_fma_f32 v240, -v174, v112, v240
	v_fma_f32 v204, v174, v114, v204
	v_fma_f32 v114, v173, v114, v240
	v_fma_f32 v112, v173, v112, v204
	v_cvt_pk_bf16_f32 v197, v114, v112
	ds_write_b32 v107, v197 offset:8416
	v_fma_f32 v241, -v174, v112, v241
	v_fma_f32 v205, v174, v114, v205
	v_fma_f32 v114, v173, v114, v241
	v_fma_f32 v112, v173, v112, v205
	v_cvt_pk_bf16_f32 v197, v114, v112
	ds_write_b32 v107, v197 offset:8688
	v_fma_f32 v8, -v174, v112, v8
	v_fma_f32 v222, v174, v114, v222
	v_fma_f32 v114, v173, v114, v8
	v_fma_f32 v112, v173, v112, v222
	v_cvt_pk_bf16_f32 v197, v114, v112
	ds_write_b32 v107, v197 offset:8960
	v_fma_f32 v9, -v174, v112, v9
	v_fma_f32 v223, v174, v114, v223
; __device__ __forceinline__ float bf_lo(unsigned w) { return __uint_as_float(w << 16); }
; __device__ __forceinline__ float bf_hi(unsigned w) { return __uint_as_float(w & 0xffff0000u); }
; __device__ __forceinline__ float gelu_t(float x) { const float u = 1.5957691216057308f * (x + 0.044715f * x * x * x); return x * sigmoid_f(u); }
; #define LAS __attribute__((address_space(3)))
; #define LDS_FENCE() asm volatile("s_waitcnt lgkmcnt(0)" ::: "memory")
; template <bool PASS2>
; __device__ __forceinline__ void s5_tile(const Ctx& C, int T, int sb_lo, int sb_hi, LAS unsigned char* lds, int wave, int lane) {
;     ...
;                 float xr = sr[gi], xi = si[gi];
; #pragma unroll
;                 for (int t = 0; t < 32; ++t) {
;                     if (sample && t == 0) { xr = s0ar; xi = s0ai; }
;                     if (sample && t == 16) { xr = s0br; xi = s0bi; }
;                     const float nr = fmaf(lr[gi], xr, fmaf(-li[gi], xi, bf_lo(bu[t]))), ni = fmaf(lr[gi], xi, fmaf(li[gi], xr, bf_hi(bu[t])));
;                     xr = nr; xi = ni;
;                     if (PASS2) {
;                         *(LAS unsigned*)(BH + t * BH_STRIDE + 2 * lane) = cvt_pk_nv(xr, xi);
;                         if (sample && (t & 15) == 15) { const int seq = 2 * sb + (t >> 4);
;                             C.out()[OFF_SRE_S + ((size_t)seq * NG + g) * NP + lane] = xr; C.out()[OFF_SIM_S + ((size_t)seq * NG + g) * NP + lane] = xi; }
;                     }
;                 }
;                 sr[gi] = xr; si[gi] = xi;
;             }
;             LDS_FENCE();
;             if (PASS2) {
; #pragma unroll
;                 for (int rb = 0; rb < 2; ++rb) {
;                     v4f acc = (v4f){0.f, 0.f, 0.f, 0.f};
; #pragma unroll
;                     for (int ks = 0; ks < 4; ++ks) {
;                         const bfx8 sa = *(const LAS bfx8*)(BH + (16 * rb + fr) * BH_STRIDE + 32 * ks + 8 * kq);
;                         acc = __builtin_amdgcn_mfma_f32_16x16x32_bf16(sa, cm[ks], acc, 0, 0, 0);
;                     }
; #pragma unroll
;                     for (int r = 0; r < 4; ++r) {
;                         LAS bf16* up = XU + (16 * rb + 4 * kq + r) * XU_STRIDE + 16 * gi + fr;
;                         const float u = __uint_as_float((unsigned)(*up) << 16);
;                         *up = f2bf(gelu_t(acc[r] + dsk[gi] * u));
;                     }
;                 }
	v_fma_f32 v114, v173, v114, v9
	v_fma_f32 v112, v173, v112, v223
	v_cvt_pk_bf16_f32 v197, v114, v112
	ds_write_b32 v107, v197 offset:9232
	v_fma_f32 v10, -v174, v112, v10
	v_fma_f32 v224, v174, v114, v224
	v_fma_f32 v114, v173, v114, v10
	v_fma_f32 v112, v173, v112, v224
	v_cvt_pk_bf16_f32 v197, v114, v112
	ds_write_b32 v107, v197 offset:9504
	v_fma_f32 v11, -v174, v112, v11
	v_fma_f32 v225, v174, v114, v225
	v_fma_f32 v114, v173, v114, v11
	v_fma_f32 v112, v173, v112, v225
	v_cvt_pk_bf16_f32 v197, v114, v112
	ds_write_b32 v107, v197 offset:9776
	v_fma_f32 v242, -v174, v112, v242
	v_fma_f32 v206, v174, v114, v206
	v_fma_f32 v114, v173, v114, v242
	v_fma_f32 v112, v173, v112, v206
	v_cvt_pk_bf16_f32 v197, v114, v112
	ds_write_b32 v107, v197 offset:10048
	v_fma_f32 v243, -v174, v112, v243
	v_fma_f32 v207, v174, v114, v207
	v_fma_f32 v114, v173, v114, v243
	v_fma_f32 v112, v173, v112, v207
	v_cvt_pk_bf16_f32 v197, v114, v112
	ds_write_b32 v107, v197 offset:10320
	v_fma_f32 v244, -v174, v112, v244
	v_fma_f32 v208, v174, v114, v208
	v_fma_f32 v114, v173, v114, v244
	v_fma_f32 v112, v173, v112, v208
	v_cvt_pk_bf16_f32 v197, v114, v112
	ds_write_b32 v107, v197 offset:10592
	v_fma_f32 v245, -v174, v112, v245
	v_fma_f32 v209, v174, v114, v209
	v_fma_f32 v114, v173, v114, v245
	v_fma_f32 v112, v173, v112, v209
	v_cvt_pk_bf16_f32 v197, v114, v112
	ds_write_b32 v107, v197 offset:10864
	v_fma_f32 v12, -v174, v112, v12
	v_fma_f32 v226, v174, v114, v226
	v_fma_f32 v114, v173, v114, v12
	v_fma_f32 v112, v173, v112, v226
	v_cvt_pk_bf16_f32 v197, v114, v112
	ds_write_b32 v107, v197 offset:11136
	v_fma_f32 v13, -v174, v112, v13
	v_fma_f32 v227, v174, v114, v227
	v_fma_f32 v114, v173, v114, v13
	v_fma_f32 v112, v173, v112, v227
	v_cvt_pk_bf16_f32 v197, v114, v112
	ds_write_b32 v107, v197 offset:11408
	v_fma_f32 v14, -v174, v112, v14
	v_fma_f32 v228, v174, v114, v228
	v_fma_f32 v114, v173, v114, v14
	v_fma_f32 v112, v173, v112, v228
	v_cvt_pk_bf16_f32 v197, v114, v112
	ds_write_b32 v107, v197 offset:11680
	v_fma_f32 v15, -v174, v112, v15
	v_fma_f32 v229, v174, v114, v229
	v_fma_f32 v114, v173, v114, v15
	v_fma_f32 v112, v173, v112, v229
	v_cvt_pk_bf16_f32 v197, v114, v112
	ds_write_b32 v107, v197 offset:11952
	v_fma_f32 v246, -v174, v112, v246
	v_fma_f32 v210, v174, v114, v210
	v_fma_f32 v114, v173, v114, v246
	v_fma_f32 v112, v173, v112, v210
	v_cvt_pk_bf16_f32 v197, v114, v112
	ds_write_b32 v107, v197 offset:12224
	v_fma_f32 v247, -v174, v112, v247
	v_fma_f32 v211, v174, v114, v211
	v_fma_f32 v114, v173, v114, v247
	v_fma_f32 v112, v173, v112, v211
	v_cvt_pk_bf16_f32 v197, v114, v112
	ds_write_b32 v107, v197 offset:12496
	v_fma_f32 v248, -v174, v112, v248
	v_fma_f32 v212, v174, v114, v212
	v_fma_f32 v114, v173, v114, v248
	v_fma_f32 v112, v173, v112, v212
	v_cvt_pk_bf16_f32 v197, v114, v112
	ds_write_b32 v107, v197 offset:12768
	v_fma_f32 v249, -v174, v112, v249
	v_fma_f32 v213, v174, v114, v213
	v_fma_f32 v114, v173, v114, v249
	v_fma_f32 v112, v173, v112, v213
	v_cvt_pk_bf16_f32 v197, v114, v112
	ds_write_b32 v107, v197 offset:13040
	s_waitcnt lgkmcnt(0)
	ds_read_b128 v[214:217], v194 offset:4608
	ds_read_b128 v[218:221], v194 offset:4672
	ds_read_b128 v[222:225], v194 offset:4736
	ds_read_b128 v[226:229], v194 offset:4800
	ds_read_b128 v[234:237], v194 offset:8960
	ds_read_b128 v[238:241], v194 offset:9024
	ds_read_b128 v[242:245], v194 offset:9088
	ds_read_b128 v[246:249], v194 offset:9152
	ds_read_u16 v8, v195
	ds_read_u16 v9, v195 offset:144
	ds_read_u16 v10, v195 offset:288
	ds_read_u16 v11, v195 offset:432
	ds_read_u16 v12, v195 offset:2304
	ds_read_u16 v13, v195 offset:2448
	ds_read_u16 v14, v195 offset:2592
	ds_read_u16 v15, v195 offset:2736
	s_waitcnt lgkmcnt(8)
	v_mfma_f32_16x16x32_bf16 v[0:3], v[214:217], v[44:47], 0
	v_mfma_f32_16x16x32_bf16 v[4:7], v[234:237], v[44:47], 0
	v_mfma_f32_16x16x32_bf16 v[0:3], v[218:221], v[40:43], v[0:3]
	v_mfma_f32_16x16x32_bf16 v[4:7], v[238:241], v[40:43], v[4:7]
	v_mfma_f32_16x16x32_bf16 v[0:3], v[222:225], v[36:39], v[0:3]
	v_mfma_f32_16x16x32_bf16 v[4:7], v[242:245], v[36:39], v[4:7]
	v_mfma_f32_16x16x32_bf16 v[0:3], v[226:229], v[32:35], v[0:3]
	v_mfma_f32_16x16x32_bf16 v[4:7], v[246:249], v[32:35], v[4:7]
	s_waitcnt lgkmcnt(0)
; #define LAS __attribute__((address_space(3)))
; template <bool PASS2>
; __device__ __forceinline__ void s5_tile(const Ctx& C, int T, int sb_lo, int sb_hi, LAS unsigned char* lds, int wave, int lane) {
;     ...
;         for (int gi = 0; gi < 4; ++gi) {
;             const int g = wave * 4 + gi, gnx = wave * 4 + ((gi + 1) & 3);
;             bfx8 bb[4], cm[4];
; #pragma unroll
;             for (int cb = 0; cb < 4; ++cb) { bb[cb] = bbn[cb]; bbn[cb] = *(const bfx8*)(BBt + ((size_t)(gnx * 128 + cb * 32 + tl)) * GN + 8 * hh); }
;             if (PASS2) {
; #pragma unroll
;                 for (int ks = 0; ks < 4; ++ks) { cm[ks] = cmn[ks]; cmn[ks] = *(const bfx8*)(CMt + ((size_t)(gnx * GN + fr)) * 128 + 32 * ks + 8 * kq); }
;             }
;             float s0ar = 0.f, s0ai = 0.f, s0br = 0.f, s0bi = 0.f;
;             if (sample) { const size_t o0 = ((size_t)(2 * sb) * NG + g) * NP + lane, o1 = o0 + (size_t)NG * NP;
;                 s0ar = C.in(2)[o0]; s0ai = C.in(3)[o0]; s0br = C.in(2)[o1]; s0bi = C.in(3)[o1]; }
;             const bfx8 a = *(const LAS bfx8*)(XU + tl * XU_STRIDE + 16 * gi + 8 * hh);
; #pragma unroll
;             for (int cb = 0; cb < 4; ++cb) {
;                 v16f acc;
; #pragma unroll
;                 for (int r = 0; r < 16; ++r) acc[r] = 0.f;
;                 acc = __builtin_amdgcn_mfma_f32_32x32x16_bf16(bb[cb], a, acc, 0, 0, 0);
; #pragma unroll
;                 for (int rg = 0; rg < 4; ++rg) { v2u w; w.x = cvt_pk_c(acc[4 * rg], acc[4 * rg + 1]); w.y = cvt_pk_c(acc[4 * rg + 2], acc[4 * rg + 3]);
;     ...
;             if (PASS2) {
; #pragma unroll
;                 for (int rb = 0; rb < 2; ++rb) {
;                     v4f acc = (v4f){0.f, 0.f, 0.f, 0.f};
; #pragma unroll
;                     for (int ks = 0; ks < 4; ++ks) {
;                         const bfx8 sa = *(const LAS bfx8*)(BH + (16 * rb + fr) * BH_STRIDE + 32 * ks + 8 * kq);
;                         acc = __builtin_amdgcn_mfma_f32_16x16x32_bf16(sa, cm[ks], acc, 0, 0, 0);
;                     }
; #pragma unroll
;                     for (int r = 0; r < 4; ++r) {
;                         LAS bf16* up = XU + (16 * rb + 4 * kq + r) * XU_STRIDE + 16 * gi + fr;
;                         const float u = __uint_as_float((unsigned)(*up) << 16);
;                         *up = f2bf(gelu_t(acc[r] + dsk[gi] * u));
;                     }
;                 }
	v_lshlrev_b32_e32 v8, 16, v8
	v_lshlrev_b32_e32 v9, 16, v9
	v_lshlrev_b32_e32 v10, 16, v10
	v_lshlrev_b32_e32 v11, 16, v11
	v_lshlrev_b32_e32 v12, 16, v12
	v_lshlrev_b32_e32 v13, 16, v13
	v_lshlrev_b32_e32 v14, 16, v14
	v_lshlrev_b32_e32 v15, 16, v15
	v_fma_f32 v0, v175, v8, v0
	v_fma_f32 v1, v175, v9, v1
	v_fma_f32 v2, v175, v10, v2
	v_fma_f32 v3, v175, v11, v3
	v_fma_f32 v4, v175, v12, v4
	v_fma_f32 v5, v175, v13, v5
	v_fma_f32 v6, v175, v14, v6
	v_fma_f32 v7, v175, v15, v7
	v_mul_f32_e32 v198, 0x3d372713, v0
	v_mul_f32_e32 v199, 0x3d372713, v1
	v_mul_f32_e32 v200, 0x3d372713, v2
	v_mul_f32_e32 v201, 0x3d372713, v3
	v_mul_f32_e32 v202, 0x3d372713, v4
	v_mul_f32_e32 v203, 0x3d372713, v5
	v_mul_f32_e32 v204, 0x3d372713, v6
	v_mul_f32_e32 v205, 0x3d372713, v7
	v_mul_f32_e32 v198, v0, v198
	v_mul_f32_e32 v199, v1, v199
	v_mul_f32_e32 v200, v2, v200
	v_mul_f32_e32 v201, v3, v201
	v_mul_f32_e32 v202, v4, v202
	v_mul_f32_e32 v203, v5, v203
	v_mul_f32_e32 v204, v6, v204
	v_mul_f32_e32 v205, v7, v205
	v_fma_f32 v198, v0, v198, v0
	v_fma_f32 v199, v1, v199, v1
	v_fma_f32 v200, v2, v200, v2
	v_fma_f32 v201, v3, v201, v3
	v_fma_f32 v202, v4, v202, v4
	v_fma_f32 v203, v5, v203, v5
	v_fma_f32 v204, v6, v204, v6
	v_fma_f32 v205, v7, v205, v7
	v_mul_f32_e32 v198, 0x3fcc422a, v198
	v_mul_f32_e32 v199, 0x3fcc422a, v199
	v_mul_f32_e32 v200, 0x3fcc422a, v200
	v_mul_f32_e32 v201, 0x3fcc422a, v201
	v_mul_f32_e32 v202, 0x3fcc422a, v202
	v_mul_f32_e32 v203, 0x3fcc422a, v203
	v_mul_f32_e32 v204, 0x3fcc422a, v204
	v_mul_f32_e32 v205, 0x3fcc422a, v205
	v_mul_f32_e32 v198, 0xbfb8aa3b, v198
	v_mul_f32_e32 v199, 0xbfb8aa3b, v199
	v_mul_f32_e32 v200, 0xbfb8aa3b, v200
	v_mul_f32_e32 v201, 0xbfb8aa3b, v201
	v_mul_f32_e32 v202, 0xbfb8aa3b, v202
	v_mul_f32_e32 v203, 0xbfb8aa3b, v203
	v_mul_f32_e32 v204, 0xbfb8aa3b, v204
	v_mul_f32_e32 v205, 0xbfb8aa3b, v205
	v_exp_f32_e32 v198, v198
	v_exp_f32_e32 v199, v199
	v_exp_f32_e32 v200, v200
	v_exp_f32_e32 v201, v201
	v_exp_f32_e32 v202, v202
	v_exp_f32_e32 v203, v203
	v_exp_f32_e32 v204, v204
	v_exp_f32_e32 v205, v205
	v_add_f32_e32 v198, 1.0, v198
	v_add_f32_e32 v199, 1.0, v199
	v_add_f32_e32 v200, 1.0, v200
	v_add_f32_e32 v201, 1.0, v201
	v_add_f32_e32 v202, 1.0, v202
	v_add_f32_e32 v203, 1.0, v203
	v_add_f32_e32 v204, 1.0, v204
	v_add_f32_e32 v205, 1.0, v205
	v_rcp_f32_e32 v198, v198
	v_rcp_f32_e32 v199, v199
	v_rcp_f32_e32 v200, v200
	v_rcp_f32_e32 v201, v201
	v_rcp_f32_e32 v202, v202
	v_rcp_f32_e32 v203, v203
	v_rcp_f32_e32 v204, v204
	v_rcp_f32_e32 v205, v205
	v_mul_f32_e32 v0, v0, v198
	v_mul_f32_e32 v1, v1, v199
	v_mul_f32_e32 v2, v2, v200
	v_mul_f32_e32 v3, v3, v201
	v_mul_f32_e32 v4, v4, v202
	v_mul_f32_e32 v5, v5, v203
	v_mul_f32_e32 v6, v6, v204
	v_mul_f32_e32 v7, v7, v205
	v_cvt_pk_bf16_f32 v0, v0, v101
	v_cvt_pk_bf16_f32 v1, v1, v101
	v_cvt_pk_bf16_f32 v2, v2, v101
	v_cvt_pk_bf16_f32 v3, v3, v101
	v_cvt_pk_bf16_f32 v4, v4, v101
	v_cvt_pk_bf16_f32 v5, v5, v101
	v_cvt_pk_bf16_f32 v6, v6, v101
	v_cvt_pk_bf16_f32 v7, v7, v101
	ds_write_b16 v195, v0
	ds_write_b16 v195, v1 offset:144
	ds_write_b16 v195, v2 offset:288
	ds_write_b16 v195, v3 offset:432
	ds_write_b16 v195, v4 offset:2304
	ds_write_b16 v195, v5 offset:2448
	ds_write_b16 v195, v6 offset:2592
	ds_write_b16 v195, v7 offset:2736
	s_waitcnt lgkmcnt(0)
	global_load_dwordx4 v[76:79], v[136:137], off
	global_load_dwordx4 v[72:75], v[138:139], off
	global_load_dwordx4 v[68:71], v[140:141], off
	global_load_dwordx4 v[64:67], v[142:143], off
	ds_read_b128 v[250:253], v192 offset:32
	s_waitcnt vmcnt(11) lgkmcnt(0)
	v_mfma_f32_32x32x16_bf16 v[0:15], v[250:253], v[92:95], 0
	global_load_dwordx4 v[44:47], v[144:145], off
	global_load_dwordx4 v[40:43], v[144:145], off offset:64
	global_load_dwordx4 v[32:35], v[144:145], off offset:128
	global_load_dwordx4 v[36:39], v[144:145], off offset:192
	s_waitcnt vmcnt(14)
	v_mfma_f32_32x32x16_bf16 v[214:229], v[250:253], v[88:91], 0
	s_waitcnt vmcnt(13)
	v_mfma_f32_32x32x16_bf16 v[234:249], v[250:253], v[84:87], 0
	s_waitcnt vmcnt(12)
	v_mfma_f32_32x32x16_bf16 v[198:213], v[250:253], v[80:83], 0
	s_nop 11
	v_permlane32_swap_b32_e32 v0, v234
	v_permlane32_swap_b32_e32 v1, v235
	v_permlane32_swap_b32_e32 v2, v236
	v_permlane32_swap_b32_e32 v3, v237
	v_permlane32_swap_b32_e32 v4, v238
	v_permlane32_swap_b32_e32 v5, v239
	v_permlane32_swap_b32_e32 v6, v240
	v_permlane32_swap_b32_e32 v7, v241
	v_permlane32_swap_b32_e32 v8, v242
	v_permlane32_swap_b32_e32 v9, v243
	v_permlane32_swap_b32_e32 v10, v244
	v_permlane32_swap_b32_e32 v11, v245
	v_permlane32_swap_b32_e32 v12, v246
	v_permlane32_swap_b32_e32 v13, v247
	v_permlane32_swap_b32_e32 v14, v248
	v_permlane32_swap_b32_e32 v15, v249
	v_permlane32_swap_b32_e32 v214, v198
	v_permlane32_swap_b32_e32 v215, v199
	v_permlane32_swap_b32_e32 v216, v200
	v_permlane32_swap_b32_e32 v217, v201
	v_permlane32_swap_b32_e32 v218, v202
	v_permlane32_swap_b32_e32 v219, v203
	v_permlane32_swap_b32_e32 v220, v204
	v_permlane32_swap_b32_e32 v221, v205
	v_permlane32_swap_b32_e32 v222, v206
	v_permlane32_swap_b32_e32 v223, v207
	v_permlane32_swap_b32_e32 v224, v208
	v_permlane32_swap_b32_e32 v225, v209
	v_permlane32_swap_b32_e32 v226, v210
	v_permlane32_swap_b32_e32 v227, v211
	v_permlane32_swap_b32_e32 v228, v212
	v_permlane32_swap_b32_e32 v229, v213
	v_fma_f32 v0, -v177, v113, v0
	v_fma_f32 v214, v177, v115, v214
	v_fma_f32 v115, v176, v115, v0
	v_fma_f32 v113, v176, v113, v214
	v_cvt_pk_bf16_f32 v197, v115, v113
	ds_write_b32 v107, v197 offset:4608
	v_fma_f32 v1, -v177, v113, v1
	v_fma_f32 v215, v177, v115, v215
	v_fma_f32 v115, v176, v115, v1
	v_fma_f32 v113, v176, v113, v215
	v_cvt_pk_bf16_f32 v197, v115, v113
; __device__ __forceinline__ float bf_lo(unsigned w) { return __uint_as_float(w << 16); }
; __device__ __forceinline__ float bf_hi(unsigned w) { return __uint_as_float(w & 0xffff0000u); }
; #define LAS __attribute__((address_space(3)))
; __device__ __forceinline__ unsigned cvt_pk_nv(float lo, float hi) { unsigned r; asm("v_cvt_pk_bf16_f32 %0, %1, %2" : "=v"(r) : "v"(lo), "v"(hi)); return r; }
;     __device__ __forceinline__ float* out() const { return (float*)karg_in(33); }
; template <bool PASS2>
; __device__ __forceinline__ void s5_tile(const Ctx& C, int T, int sb_lo, int sb_hi, LAS unsigned char* lds, int wave, int lane) {
;     ...
;                 float xr = sr[gi], xi = si[gi];
; #pragma unroll
;                 for (int t = 0; t < 32; ++t) {
;                     if (sample && t == 0) { xr = s0ar; xi = s0ai; }
;                     if (sample && t == 16) { xr = s0br; xi = s0bi; }
;                     const float nr = fmaf(lr[gi], xr, fmaf(-li[gi], xi, bf_lo(bu[t]))), ni = fmaf(lr[gi], xi, fmaf(li[gi], xr, bf_hi(bu[t])));
;                     xr = nr; xi = ni;
;                     if (PASS2) {
;                         *(LAS unsigned*)(BH + t * BH_STRIDE + 2 * lane) = cvt_pk_nv(xr, xi);
;                         if (sample && (t & 15) == 15) { const int seq = 2 * sb + (t >> 4);
;                             C.out()[OFF_SRE_S + ((size_t)seq * NG + g) * NP + lane] = xr; C.out()[OFF_SIM_S + ((size_t)seq * NG + g) * NP + lane] = xi; }
;                     }
;                 }
;                 sr[gi] = xr; si[gi] = xi;
	ds_write_b32 v107, v197 offset:4880
	v_fma_f32 v2, -v177, v113, v2
	v_fma_f32 v216, v177, v115, v216
	v_fma_f32 v115, v176, v115, v2
	v_fma_f32 v113, v176, v113, v216
	v_cvt_pk_bf16_f32 v197, v115, v113
	ds_write_b32 v107, v197 offset:5152
	v_fma_f32 v3, -v177, v113, v3
	v_fma_f32 v217, v177, v115, v217
	v_fma_f32 v115, v176, v115, v3
	v_fma_f32 v113, v176, v113, v217
	v_cvt_pk_bf16_f32 v197, v115, v113
	ds_write_b32 v107, v197 offset:5424
	v_fma_f32 v234, -v177, v113, v234
	v_fma_f32 v198, v177, v115, v198
	v_fma_f32 v115, v176, v115, v234
	v_fma_f32 v113, v176, v113, v198
	v_cvt_pk_bf16_f32 v197, v115, v113
	ds_write_b32 v107, v197 offset:5696
	v_fma_f32 v235, -v177, v113, v235
	v_fma_f32 v199, v177, v115, v199
	v_fma_f32 v115, v176, v115, v235
	v_fma_f32 v113, v176, v113, v199
	v_cvt_pk_bf16_f32 v197, v115, v113
	ds_write_b32 v107, v197 offset:5968
	v_fma_f32 v236, -v177, v113, v236
	v_fma_f32 v200, v177, v115, v200
	v_fma_f32 v115, v176, v115, v236
	v_fma_f32 v113, v176, v113, v200
	v_cvt_pk_bf16_f32 v197, v115, v113
	ds_write_b32 v107, v197 offset:6240
	v_fma_f32 v237, -v177, v113, v237
	v_fma_f32 v201, v177, v115, v201
	v_fma_f32 v115, v176, v115, v237
	v_fma_f32 v113, v176, v113, v201
	v_cvt_pk_bf16_f32 v197, v115, v113
	ds_write_b32 v107, v197 offset:6512
	v_fma_f32 v4, -v177, v113, v4
	v_fma_f32 v218, v177, v115, v218
	v_fma_f32 v115, v176, v115, v4
	v_fma_f32 v113, v176, v113, v218
	v_cvt_pk_bf16_f32 v197, v115, v113
	ds_write_b32 v107, v197 offset:6784
	v_fma_f32 v5, -v177, v113, v5
	v_fma_f32 v219, v177, v115, v219
	v_fma_f32 v115, v176, v115, v5
	v_fma_f32 v113, v176, v113, v219
	v_cvt_pk_bf16_f32 v197, v115, v113
	ds_write_b32 v107, v197 offset:7056
	v_fma_f32 v6, -v177, v113, v6
	v_fma_f32 v220, v177, v115, v220
	v_fma_f32 v115, v176, v115, v6
	v_fma_f32 v113, v176, v113, v220
	v_cvt_pk_bf16_f32 v197, v115, v113
	ds_write_b32 v107, v197 offset:7328
	v_fma_f32 v7, -v177, v113, v7
	v_fma_f32 v221, v177, v115, v221
	v_fma_f32 v115, v176, v115, v7
	v_fma_f32 v113, v176, v113, v221
	v_cvt_pk_bf16_f32 v197, v115, v113
	ds_write_b32 v107, v197 offset:7600
	v_fma_f32 v238, -v177, v113, v238
	v_fma_f32 v202, v177, v115, v202
	v_fma_f32 v115, v176, v115, v238
	v_fma_f32 v113, v176, v113, v202
	v_cvt_pk_bf16_f32 v197, v115, v113
	ds_write_b32 v107, v197 offset:7872
	v_fma_f32 v239, -v177, v113, v239
	v_fma_f32 v203, v177, v115, v203
	v_fma_f32 v115, v176, v115, v239
	v_fma_f32 v113, v176, v113, v203
	v_cvt_pk_bf16_f32 v197, v115, v113
	ds_write_b32 v107, v197 offset:8144
	v_fma_f32 v240, -v177, v113, v240
	v_fma_f32 v204, v177, v115, v204
	v_fma_f32 v115, v176, v115, v240
	v_fma_f32 v113, v176, v113, v204
	v_cvt_pk_bf16_f32 v197, v115, v113
	ds_write_b32 v107, v197 offset:8416
	v_fma_f32 v241, -v177, v113, v241
	v_fma_f32 v205, v177, v115, v205
	v_fma_f32 v115, v176, v115, v241
	v_fma_f32 v113, v176, v113, v205
	v_cvt_pk_bf16_f32 v197, v115, v113
	ds_write_b32 v107, v197 offset:8688
	v_fma_f32 v8, -v177, v113, v8
	v_fma_f32 v222, v177, v115, v222
	v_fma_f32 v115, v176, v115, v8
	v_fma_f32 v113, v176, v113, v222
	v_cvt_pk_bf16_f32 v197, v115, v113
	ds_write_b32 v107, v197 offset:8960
	v_fma_f32 v9, -v177, v113, v9
	v_fma_f32 v223, v177, v115, v223
	v_fma_f32 v115, v176, v115, v9
	v_fma_f32 v113, v176, v113, v223
	v_cvt_pk_bf16_f32 v197, v115, v113
	ds_write_b32 v107, v197 offset:9232
	v_fma_f32 v10, -v177, v113, v10
	v_fma_f32 v224, v177, v115, v224
	v_fma_f32 v115, v176, v115, v10
	v_fma_f32 v113, v176, v113, v224
	v_cvt_pk_bf16_f32 v197, v115, v113
	ds_write_b32 v107, v197 offset:9504
	v_fma_f32 v11, -v177, v113, v11
	v_fma_f32 v225, v177, v115, v225
	v_fma_f32 v115, v176, v115, v11
	v_fma_f32 v113, v176, v113, v225
	v_cvt_pk_bf16_f32 v197, v115, v113
	ds_write_b32 v107, v197 offset:9776
	v_fma_f32 v242, -v177, v113, v242
	v_fma_f32 v206, v177, v115, v206
	v_fma_f32 v115, v176, v115, v242
	v_fma_f32 v113, v176, v113, v206
	v_cvt_pk_bf16_f32 v197, v115, v113
	ds_write_b32 v107, v197 offset:10048
	v_fma_f32 v243, -v177, v113, v243
	v_fma_f32 v207, v177, v115, v207
	v_fma_f32 v115, v176, v115, v243
	v_fma_f32 v113, v176, v113, v207
	v_cvt_pk_bf16_f32 v197, v115, v113
	ds_write_b32 v107, v197 offset:10320
	v_fma_f32 v244, -v177, v113, v244
	v_fma_f32 v208, v177, v115, v208
	v_fma_f32 v115, v176, v115, v244
	v_fma_f32 v113, v176, v113, v208
	v_cvt_pk_bf16_f32 v197, v115, v113
	ds_write_b32 v107, v197 offset:10592
	v_fma_f32 v245, -v177, v113, v245
	v_fma_f32 v209, v177, v115, v209
	v_fma_f32 v115, v176, v115, v245
	v_fma_f32 v113, v176, v113, v209
	v_cvt_pk_bf16_f32 v197, v115, v113
	ds_write_b32 v107, v197 offset:10864
	v_fma_f32 v12, -v177, v113, v12
	v_fma_f32 v226, v177, v115, v226
	v_fma_f32 v115, v176, v115, v12
	v_fma_f32 v113, v176, v113, v226
	v_cvt_pk_bf16_f32 v197, v115, v113
	ds_write_b32 v107, v197 offset:11136
	v_fma_f32 v13, -v177, v113, v13
	v_fma_f32 v227, v177, v115, v227
	v_fma_f32 v115, v176, v115, v13
	v_fma_f32 v113, v176, v113, v227
	v_cvt_pk_bf16_f32 v197, v115, v113
	ds_write_b32 v107, v197 offset:11408
	v_fma_f32 v14, -v177, v113, v14
	v_fma_f32 v228, v177, v115, v228
	v_fma_f32 v115, v176, v115, v14
	v_fma_f32 v113, v176, v113, v228
	v_cvt_pk_bf16_f32 v197, v115, v113
	ds_write_b32 v107, v197 offset:11680
	v_fma_f32 v15, -v177, v113, v15
	v_fma_f32 v229, v177, v115, v229
	v_fma_f32 v115, v176, v115, v15
	v_fma_f32 v113, v176, v113, v229
	v_cvt_pk_bf16_f32 v197, v115, v113
	ds_write_b32 v107, v197 offset:11952
	v_fma_f32 v246, -v177, v113, v246
	v_fma_f32 v210, v177, v115, v210
	v_fma_f32 v115, v176, v115, v246
	v_fma_f32 v113, v176, v113, v210
	v_cvt_pk_bf16_f32 v197, v115, v113
	ds_write_b32 v107, v197 offset:12224
	v_fma_f32 v247, -v177, v113, v247
	v_fma_f32 v211, v177, v115, v211
	v_fma_f32 v115, v176, v115, v247
	v_fma_f32 v113, v176, v113, v211
	v_cvt_pk_bf16_f32 v197, v115, v113
	ds_write_b32 v107, v197 offset:12496
	v_fma_f32 v248, -v177, v113, v248
	v_fma_f32 v212, v177, v115, v212
	v_fma_f32 v115, v176, v115, v248
	v_fma_f32 v113, v176, v113, v212
	v_cvt_pk_bf16_f32 v197, v115, v113
	ds_write_b32 v107, v197 offset:12768
	v_fma_f32 v249, -v177, v113, v249
	v_fma_f32 v213, v177, v115, v213
	v_fma_f32 v115, v176, v115, v249
	v_fma_f32 v113, v176, v113, v213
	v_cvt_pk_bf16_f32 v197, v115, v113
	ds_write_b32 v107, v197 offset:13040
	s_waitcnt lgkmcnt(0)
; __device__ __forceinline__ float gelu_t(float x) { const float u = 1.5957691216057308f * (x + 0.044715f * x * x * x); return x * sigmoid_f(u); }
; #define LAS __attribute__((address_space(3)))
; template <bool PASS2>
; __device__ __forceinline__ void s5_tile(const Ctx& C, int T, int sb_lo, int sb_hi, LAS unsigned char* lds, int wave, int lane) {
;     ...
;         for (int gi = 0; gi < 4; ++gi) {
;             const int g = wave * 4 + gi, gnx = wave * 4 + ((gi + 1) & 3);
;             bfx8 bb[4], cm[4];
; #pragma unroll
;             for (int cb = 0; cb < 4; ++cb) { bb[cb] = bbn[cb]; bbn[cb] = *(const bfx8*)(BBt + ((size_t)(gnx * 128 + cb * 32 + tl)) * GN + 8 * hh); }
;             if (PASS2) {
; #pragma unroll
;                 for (int ks = 0; ks < 4; ++ks) { cm[ks] = cmn[ks]; cmn[ks] = *(const bfx8*)(CMt + ((size_t)(gnx * GN + fr)) * 128 + 32 * ks + 8 * kq); }
;             }
;             float s0ar = 0.f, s0ai = 0.f, s0br = 0.f, s0bi = 0.f;
;             if (sample) { const size_t o0 = ((size_t)(2 * sb) * NG + g) * NP + lane, o1 = o0 + (size_t)NG * NP;
;                 s0ar = C.in(2)[o0]; s0ai = C.in(3)[o0]; s0br = C.in(2)[o1]; s0bi = C.in(3)[o1]; }
;             const bfx8 a = *(const LAS bfx8*)(XU + tl * XU_STRIDE + 16 * gi + 8 * hh);
; #pragma unroll
;             for (int cb = 0; cb < 4; ++cb) {
;                 v16f acc;
; #pragma unroll
;                 for (int r = 0; r < 16; ++r) acc[r] = 0.f;
;                 acc = __builtin_amdgcn_mfma_f32_32x32x16_bf16(bb[cb], a, acc, 0, 0, 0);
;     ...
;             if (PASS2) {
; #pragma unroll
;                 for (int rb = 0; rb < 2; ++rb) {
;                     v4f acc = (v4f){0.f, 0.f, 0.f, 0.f};
; #pragma unroll
;                     for (int ks = 0; ks < 4; ++ks) {
;                         const bfx8 sa = *(const LAS bfx8*)(BH + (16 * rb + fr) * BH_STRIDE + 32 * ks + 8 * kq);
;                         acc = __builtin_amdgcn_mfma_f32_16x16x32_bf16(sa, cm[ks], acc, 0, 0, 0);
;                     }
; #pragma unroll
;                     for (int r = 0; r < 4; ++r) {
;                         LAS bf16* up = XU + (16 * rb + 4 * kq + r) * XU_STRIDE + 16 * gi + fr;
;                         const float u = __uint_as_float((unsigned)(*up) << 16);
;                         *up = f2bf(gelu_t(acc[r] + dsk[gi] * u));
;                     }
;                 }
	ds_read_b128 v[214:217], v194 offset:4608
	ds_read_b128 v[218:221], v194 offset:4672
	ds_read_b128 v[222:225], v194 offset:4736
	ds_read_b128 v[226:229], v194 offset:4800
	ds_read_b128 v[234:237], v194 offset:8960
	ds_read_b128 v[238:241], v194 offset:9024
	ds_read_b128 v[242:245], v194 offset:9088
	ds_read_b128 v[246:249], v194 offset:9152
	ds_read_u16 v8, v195 offset:32
	ds_read_u16 v9, v195 offset:176
	ds_read_u16 v10, v195 offset:320
	ds_read_u16 v11, v195 offset:464
	ds_read_u16 v12, v195 offset:2336
	ds_read_u16 v13, v195 offset:2480
	ds_read_u16 v14, v195 offset:2624
	ds_read_u16 v15, v195 offset:2768
	s_waitcnt vmcnt(8) lgkmcnt(8)
	v_mfma_f32_16x16x32_bf16 v[0:3], v[214:217], v[60:63], 0
	v_mfma_f32_16x16x32_bf16 v[4:7], v[234:237], v[60:63], 0
	v_mfma_f32_16x16x32_bf16 v[0:3], v[218:221], v[56:59], v[0:3]
	v_mfma_f32_16x16x32_bf16 v[4:7], v[238:241], v[56:59], v[4:7]
	v_mfma_f32_16x16x32_bf16 v[0:3], v[222:225], v[48:51], v[0:3]
	v_mfma_f32_16x16x32_bf16 v[4:7], v[242:245], v[48:51], v[4:7]
	v_mfma_f32_16x16x32_bf16 v[0:3], v[226:229], v[52:55], v[0:3]
	v_mfma_f32_16x16x32_bf16 v[4:7], v[246:249], v[52:55], v[4:7]
	s_waitcnt lgkmcnt(0)
	v_lshlrev_b32_e32 v8, 16, v8
	v_lshlrev_b32_e32 v9, 16, v9
	v_lshlrev_b32_e32 v10, 16, v10
	v_lshlrev_b32_e32 v11, 16, v11
	v_lshlrev_b32_e32 v12, 16, v12
	v_lshlrev_b32_e32 v13, 16, v13
	v_lshlrev_b32_e32 v14, 16, v14
	v_lshlrev_b32_e32 v15, 16, v15
	v_fma_f32 v0, v178, v8, v0
	v_fma_f32 v1, v178, v9, v1
	v_fma_f32 v2, v178, v10, v2
	v_fma_f32 v3, v178, v11, v3
	v_fma_f32 v4, v178, v12, v4
	v_fma_f32 v5, v178, v13, v5
	v_fma_f32 v6, v178, v14, v6
	v_fma_f32 v7, v178, v15, v7
	v_mul_f32_e32 v198, 0x3d372713, v0
	v_mul_f32_e32 v199, 0x3d372713, v1
	v_mul_f32_e32 v200, 0x3d372713, v2
	v_mul_f32_e32 v201, 0x3d372713, v3
	v_mul_f32_e32 v202, 0x3d372713, v4
	v_mul_f32_e32 v203, 0x3d372713, v5
	v_mul_f32_e32 v204, 0x3d372713, v6
	v_mul_f32_e32 v205, 0x3d372713, v7
	v_mul_f32_e32 v198, v0, v198
	v_mul_f32_e32 v199, v1, v199
	v_mul_f32_e32 v200, v2, v200
	v_mul_f32_e32 v201, v3, v201
	v_mul_f32_e32 v202, v4, v202
	v_mul_f32_e32 v203, v5, v203
	v_mul_f32_e32 v204, v6, v204
	v_mul_f32_e32 v205, v7, v205
	v_fma_f32 v198, v0, v198, v0
	v_fma_f32 v199, v1, v199, v1
	v_fma_f32 v200, v2, v200, v2
	v_fma_f32 v201, v3, v201, v3
	v_fma_f32 v202, v4, v202, v4
	v_fma_f32 v203, v5, v203, v5
	v_fma_f32 v204, v6, v204, v6
	v_fma_f32 v205, v7, v205, v7
	v_mul_f32_e32 v198, 0x3fcc422a, v198
	v_mul_f32_e32 v199, 0x3fcc422a, v199
	v_mul_f32_e32 v200, 0x3fcc422a, v200
	v_mul_f32_e32 v201, 0x3fcc422a, v201
	v_mul_f32_e32 v202, 0x3fcc422a, v202
	v_mul_f32_e32 v203, 0x3fcc422a, v203
	v_mul_f32_e32 v204, 0x3fcc422a, v204
	v_mul_f32_e32 v205, 0x3fcc422a, v205
	v_mul_f32_e32 v198, 0xbfb8aa3b, v198
	v_mul_f32_e32 v199, 0xbfb8aa3b, v199
	v_mul_f32_e32 v200, 0xbfb8aa3b, v200
	v_mul_f32_e32 v201, 0xbfb8aa3b, v201
	v_mul_f32_e32 v202, 0xbfb8aa3b, v202
	v_mul_f32_e32 v203, 0xbfb8aa3b, v203
	v_mul_f32_e32 v204, 0xbfb8aa3b, v204
	v_mul_f32_e32 v205, 0xbfb8aa3b, v205
	v_exp_f32_e32 v198, v198
	v_exp_f32_e32 v199, v199
	v_exp_f32_e32 v200, v200
	v_exp_f32_e32 v201, v201
	v_exp_f32_e32 v202, v202
	v_exp_f32_e32 v203, v203
	v_exp_f32_e32 v204, v204
	v_exp_f32_e32 v205, v205
	v_add_f32_e32 v198, 1.0, v198
	v_add_f32_e32 v199, 1.0, v199
	v_add_f32_e32 v200, 1.0, v200
	v_add_f32_e32 v201, 1.0, v201
	v_add_f32_e32 v202, 1.0, v202
	v_add_f32_e32 v203, 1.0, v203
	v_add_f32_e32 v204, 1.0, v204
	v_add_f32_e32 v205, 1.0, v205
	v_rcp_f32_e32 v198, v198
	v_rcp_f32_e32 v199, v199
	v_rcp_f32_e32 v200, v200
	v_rcp_f32_e32 v201, v201
	v_rcp_f32_e32 v202, v202
	v_rcp_f32_e32 v203, v203
	v_rcp_f32_e32 v204, v204
	v_rcp_f32_e32 v205, v205
	v_mul_f32_e32 v0, v0, v198
	v_mul_f32_e32 v1, v1, v199
	v_mul_f32_e32 v2, v2, v200
	v_mul_f32_e32 v3, v3, v201
	v_mul_f32_e32 v4, v4, v202
	v_mul_f32_e32 v5, v5, v203
	v_mul_f32_e32 v6, v6, v204
	v_mul_f32_e32 v7, v7, v205
	v_cvt_pk_bf16_f32 v0, v0, v101
	v_cvt_pk_bf16_f32 v1, v1, v101
	v_cvt_pk_bf16_f32 v2, v2, v101
	v_cvt_pk_bf16_f32 v3, v3, v101
	v_cvt_pk_bf16_f32 v4, v4, v101
	v_cvt_pk_bf16_f32 v5, v5, v101
	v_cvt_pk_bf16_f32 v6, v6, v101
	v_cvt_pk_bf16_f32 v7, v7, v101
	ds_write_b16 v195, v0 offset:32
	ds_write_b16 v195, v1 offset:176
	ds_write_b16 v195, v2 offset:320
	ds_write_b16 v195, v3 offset:464
	ds_write_b16 v195, v4 offset:2336
	ds_write_b16 v195, v5 offset:2480
	ds_write_b16 v195, v6 offset:2624
	ds_write_b16 v195, v7 offset:2768
	s_waitcnt lgkmcnt(0)
	global_load_dwordx4 v[92:95], v[146:147], off
	global_load_dwordx4 v[88:91], v[148:149], off
	global_load_dwordx4 v[84:87], v[150:151], off
	global_load_dwordx4 v[80:83], v[152:153], off
	ds_read_b128 v[250:253], v192 offset:64
	s_waitcnt vmcnt(11) lgkmcnt(0)
	v_mfma_f32_32x32x16_bf16 v[0:15], v[250:253], v[76:79], 0
	global_load_dwordx4 v[60:63], v[154:155], off
	global_load_dwordx4 v[56:59], v[154:155], off offset:64
	global_load_dwordx4 v[48:51], v[154:155], off offset:128
	global_load_dwordx4 v[52:55], v[154:155], off offset:192
	s_waitcnt vmcnt(14)
	v_mfma_f32_32x32x16_bf16 v[214:229], v[250:253], v[72:75], 0
	s_waitcnt vmcnt(13)
	v_mfma_f32_32x32x16_bf16 v[234:249], v[250:253], v[68:71], 0
	s_waitcnt vmcnt(12)
; __device__ __forceinline__ float bf_lo(unsigned w) { return __uint_as_float(w << 16); }
; __device__ __forceinline__ float bf_hi(unsigned w) { return __uint_as_float(w & 0xffff0000u); }
; #define LAS __attribute__((address_space(3)))
; #define LDS_FENCE() asm volatile("s_waitcnt lgkmcnt(0)" ::: "memory")
; __device__ __forceinline__ unsigned cvt_pk_nv(float lo, float hi) { unsigned r; asm("v_cvt_pk_bf16_f32 %0, %1, %2" : "=v"(r) : "v"(lo), "v"(hi)); return r; }
; template <bool PASS2>
; __device__ __forceinline__ void s5_tile(const Ctx& C, int T, int sb_lo, int sb_hi, LAS unsigned char* lds, int wave, int lane) {
;     ...
;             const bfx8 a = *(const LAS bfx8*)(XU + tl * XU_STRIDE + 16 * gi + 8 * hh);
; #pragma unroll
;             for (int cb = 0; cb < 4; ++cb) {
;                 v16f acc;
; #pragma unroll
;                 for (int r = 0; r < 16; ++r) acc[r] = 0.f;
;                 acc = __builtin_amdgcn_mfma_f32_32x32x16_bf16(bb[cb], a, acc, 0, 0, 0);
; #pragma unroll
;                 for (int rg = 0; rg < 4; ++rg) { v2u w; w.x = cvt_pk_c(acc[4 * rg], acc[4 * rg + 1]); w.y = cvt_pk_c(acc[4 * rg + 2], acc[4 * rg + 3]);
;                     *(LAS v2u*)(BH + tl * BH_STRIDE + cb * 32 + 8 * rg + 4 * hh) = w; }
;             }
;             LDS_FENCE();
;             {
;                 unsigned bu[32];
; #pragma unroll
;                 for (int t = 0; t < 32; ++t) bu[t] = *(const LAS unsigned*)(BH + t * BH_STRIDE + 2 * lane);
;                 LDS_FENCE();
;                 float xr = sr[gi], xi = si[gi];
; #pragma unroll
;                 for (int t = 0; t < 32; ++t) {
;                     if (sample && t == 0) { xr = s0ar; xi = s0ai; }
;                     if (sample && t == 16) { xr = s0br; xi = s0bi; }
;                     const float nr = fmaf(lr[gi], xr, fmaf(-li[gi], xi, bf_lo(bu[t]))), ni = fmaf(lr[gi], xi, fmaf(li[gi], xr, bf_hi(bu[t])));
;                     xr = nr; xi = ni;
;                     if (PASS2) {
;                         *(LAS unsigned*)(BH + t * BH_STRIDE + 2 * lane) = cvt_pk_nv(xr, xi);
;                         if (sample && (t & 15) == 15) { const int seq = 2 * sb + (t >> 4);
;                             C.out()[OFF_SRE_S + ((size_t)seq * NG + g) * NP + lane] = xr; C.out()[OFF_SIM_S + ((size_t)seq * NG + g) * NP + lane] = xi; }
;                     }
;                 }
;                 sr[gi] = xr; si[gi] = xi;
	v_mfma_f32_32x32x16_bf16 v[198:213], v[250:253], v[64:67], 0
	s_nop 11
	v_permlane32_swap_b32_e32 v0, v234
	v_permlane32_swap_b32_e32 v1, v235
	v_permlane32_swap_b32_e32 v2, v236
	v_permlane32_swap_b32_e32 v3, v237
	v_permlane32_swap_b32_e32 v4, v238
	v_permlane32_swap_b32_e32 v5, v239
	v_permlane32_swap_b32_e32 v6, v240
	v_permlane32_swap_b32_e32 v7, v241
	v_permlane32_swap_b32_e32 v8, v242
	v_permlane32_swap_b32_e32 v9, v243
	v_permlane32_swap_b32_e32 v10, v244
	v_permlane32_swap_b32_e32 v11, v245
	v_permlane32_swap_b32_e32 v12, v246
	v_permlane32_swap_b32_e32 v13, v247
	v_permlane32_swap_b32_e32 v14, v248
	v_permlane32_swap_b32_e32 v15, v249
	v_permlane32_swap_b32_e32 v214, v198
	v_permlane32_swap_b32_e32 v215, v199
	v_permlane32_swap_b32_e32 v216, v200
	v_permlane32_swap_b32_e32 v217, v201
	v_permlane32_swap_b32_e32 v218, v202
	v_permlane32_swap_b32_e32 v219, v203
	v_permlane32_swap_b32_e32 v220, v204
	v_permlane32_swap_b32_e32 v221, v205
	v_permlane32_swap_b32_e32 v222, v206
	v_permlane32_swap_b32_e32 v223, v207
	v_permlane32_swap_b32_e32 v224, v208
	v_permlane32_swap_b32_e32 v225, v209
	v_permlane32_swap_b32_e32 v226, v210
	v_permlane32_swap_b32_e32 v227, v211
	v_permlane32_swap_b32_e32 v228, v212
	v_permlane32_swap_b32_e32 v229, v213
	v_fma_f32 v0, -v180, v108, v0
	v_fma_f32 v214, v180, v110, v214
	v_fma_f32 v110, v179, v110, v0
	v_fma_f32 v108, v179, v108, v214
	v_cvt_pk_bf16_f32 v197, v110, v108
	ds_write_b32 v107, v197 offset:4608
	v_fma_f32 v1, -v180, v108, v1
	v_fma_f32 v215, v180, v110, v215
	v_fma_f32 v110, v179, v110, v1
	v_fma_f32 v108, v179, v108, v215
	v_cvt_pk_bf16_f32 v197, v110, v108
	ds_write_b32 v107, v197 offset:4880
	v_fma_f32 v2, -v180, v108, v2
	v_fma_f32 v216, v180, v110, v216
	v_fma_f32 v110, v179, v110, v2
	v_fma_f32 v108, v179, v108, v216
	v_cvt_pk_bf16_f32 v197, v110, v108
	ds_write_b32 v107, v197 offset:5152
	v_fma_f32 v3, -v180, v108, v3
	v_fma_f32 v217, v180, v110, v217
	v_fma_f32 v110, v179, v110, v3
	v_fma_f32 v108, v179, v108, v217
	v_cvt_pk_bf16_f32 v197, v110, v108
	ds_write_b32 v107, v197 offset:5424
	v_fma_f32 v234, -v180, v108, v234
	v_fma_f32 v198, v180, v110, v198
	v_fma_f32 v110, v179, v110, v234
	v_fma_f32 v108, v179, v108, v198
	v_cvt_pk_bf16_f32 v197, v110, v108
	ds_write_b32 v107, v197 offset:5696
	v_fma_f32 v235, -v180, v108, v235
	v_fma_f32 v199, v180, v110, v199
	v_fma_f32 v110, v179, v110, v235
	v_fma_f32 v108, v179, v108, v199
	v_cvt_pk_bf16_f32 v197, v110, v108
	ds_write_b32 v107, v197 offset:5968
	v_fma_f32 v236, -v180, v108, v236
	v_fma_f32 v200, v180, v110, v200
	v_fma_f32 v110, v179, v110, v236
	v_fma_f32 v108, v179, v108, v200
	v_cvt_pk_bf16_f32 v197, v110, v108
	ds_write_b32 v107, v197 offset:6240
	v_fma_f32 v237, -v180, v108, v237
	v_fma_f32 v201, v180, v110, v201
	v_fma_f32 v110, v179, v110, v237
	v_fma_f32 v108, v179, v108, v201
	v_cvt_pk_bf16_f32 v197, v110, v108
	ds_write_b32 v107, v197 offset:6512
	v_fma_f32 v4, -v180, v108, v4
	v_fma_f32 v218, v180, v110, v218
	v_fma_f32 v110, v179, v110, v4
	v_fma_f32 v108, v179, v108, v218
	v_cvt_pk_bf16_f32 v197, v110, v108
	ds_write_b32 v107, v197 offset:6784
	v_fma_f32 v5, -v180, v108, v5
	v_fma_f32 v219, v180, v110, v219
	v_fma_f32 v110, v179, v110, v5
	v_fma_f32 v108, v179, v108, v219
	v_cvt_pk_bf16_f32 v197, v110, v108
	ds_write_b32 v107, v197 offset:7056
	v_fma_f32 v6, -v180, v108, v6
	v_fma_f32 v220, v180, v110, v220
	v_fma_f32 v110, v179, v110, v6
	v_fma_f32 v108, v179, v108, v220
	v_cvt_pk_bf16_f32 v197, v110, v108
	ds_write_b32 v107, v197 offset:7328
	v_fma_f32 v7, -v180, v108, v7
	v_fma_f32 v221, v180, v110, v221
	v_fma_f32 v110, v179, v110, v7
	v_fma_f32 v108, v179, v108, v221
	v_cvt_pk_bf16_f32 v197, v110, v108
	ds_write_b32 v107, v197 offset:7600
	v_fma_f32 v238, -v180, v108, v238
	v_fma_f32 v202, v180, v110, v202
	v_fma_f32 v110, v179, v110, v238
	v_fma_f32 v108, v179, v108, v202
	v_cvt_pk_bf16_f32 v197, v110, v108
	ds_write_b32 v107, v197 offset:7872
	v_fma_f32 v239, -v180, v108, v239
	v_fma_f32 v203, v180, v110, v203
	v_fma_f32 v110, v179, v110, v239
	v_fma_f32 v108, v179, v108, v203
	v_cvt_pk_bf16_f32 v197, v110, v108
	ds_write_b32 v107, v197 offset:8144
	v_fma_f32 v240, -v180, v108, v240
	v_fma_f32 v204, v180, v110, v204
	v_fma_f32 v110, v179, v110, v240
	v_fma_f32 v108, v179, v108, v204
	v_cvt_pk_bf16_f32 v197, v110, v108
	ds_write_b32 v107, v197 offset:8416
	v_fma_f32 v241, -v180, v108, v241
	v_fma_f32 v205, v180, v110, v205
	v_fma_f32 v110, v179, v110, v241
	v_fma_f32 v108, v179, v108, v205
	v_cvt_pk_bf16_f32 v197, v110, v108
	ds_write_b32 v107, v197 offset:8688
	v_fma_f32 v8, -v180, v108, v8
	v_fma_f32 v222, v180, v110, v222
	v_fma_f32 v110, v179, v110, v8
	v_fma_f32 v108, v179, v108, v222
	v_cvt_pk_bf16_f32 v197, v110, v108
	ds_write_b32 v107, v197 offset:8960
	v_fma_f32 v9, -v180, v108, v9
	v_fma_f32 v223, v180, v110, v223
	v_fma_f32 v110, v179, v110, v9
	v_fma_f32 v108, v179, v108, v223
	v_cvt_pk_bf16_f32 v197, v110, v108
	ds_write_b32 v107, v197 offset:9232
	v_fma_f32 v10, -v180, v108, v10
	v_fma_f32 v224, v180, v110, v224
	v_fma_f32 v110, v179, v110, v10
	v_fma_f32 v108, v179, v108, v224
	v_cvt_pk_bf16_f32 v197, v110, v108
	ds_write_b32 v107, v197 offset:9504
	v_fma_f32 v11, -v180, v108, v11
	v_fma_f32 v225, v180, v110, v225
	v_fma_f32 v110, v179, v110, v11
	v_fma_f32 v108, v179, v108, v225
	v_cvt_pk_bf16_f32 v197, v110, v108
	ds_write_b32 v107, v197 offset:9776
	v_fma_f32 v242, -v180, v108, v242
	v_fma_f32 v206, v180, v110, v206
	v_fma_f32 v110, v179, v110, v242
	v_fma_f32 v108, v179, v108, v206
	v_cvt_pk_bf16_f32 v197, v110, v108
	ds_write_b32 v107, v197 offset:10048
	v_fma_f32 v243, -v180, v108, v243
; __device__ __forceinline__ float bf_lo(unsigned w) { return __uint_as_float(w << 16); }
; __device__ __forceinline__ float bf_hi(unsigned w) { return __uint_as_float(w & 0xffff0000u); }
; __device__ __forceinline__ float gelu_t(float x) { const float u = 1.5957691216057308f * (x + 0.044715f * x * x * x); return x * sigmoid_f(u); }
; #define LAS __attribute__((address_space(3)))
; #define LDS_FENCE() asm volatile("s_waitcnt lgkmcnt(0)" ::: "memory")
; template <bool PASS2>
; __device__ __forceinline__ void s5_tile(const Ctx& C, int T, int sb_lo, int sb_hi, LAS unsigned char* lds, int wave, int lane) {
;     ...
;                 float xr = sr[gi], xi = si[gi];
; #pragma unroll
;                 for (int t = 0; t < 32; ++t) {
;                     if (sample && t == 0) { xr = s0ar; xi = s0ai; }
;                     if (sample && t == 16) { xr = s0br; xi = s0bi; }
;                     const float nr = fmaf(lr[gi], xr, fmaf(-li[gi], xi, bf_lo(bu[t]))), ni = fmaf(lr[gi], xi, fmaf(li[gi], xr, bf_hi(bu[t])));
;                     xr = nr; xi = ni;
;                     if (PASS2) {
;                         *(LAS unsigned*)(BH + t * BH_STRIDE + 2 * lane) = cvt_pk_nv(xr, xi);
;                         if (sample && (t & 15) == 15) { const int seq = 2 * sb + (t >> 4);
;                             C.out()[OFF_SRE_S + ((size_t)seq * NG + g) * NP + lane] = xr; C.out()[OFF_SIM_S + ((size_t)seq * NG + g) * NP + lane] = xi; }
;                     }
;                 }
;                 sr[gi] = xr; si[gi] = xi;
;             }
;             LDS_FENCE();
;             if (PASS2) {
; #pragma unroll
;                 for (int rb = 0; rb < 2; ++rb) {
;                     v4f acc = (v4f){0.f, 0.f, 0.f, 0.f};
; #pragma unroll
;                     for (int ks = 0; ks < 4; ++ks) {
;                         const bfx8 sa = *(const LAS bfx8*)(BH + (16 * rb + fr) * BH_STRIDE + 32 * ks + 8 * kq);
;                         acc = __builtin_amdgcn_mfma_f32_16x16x32_bf16(sa, cm[ks], acc, 0, 0, 0);
;                     }
; #pragma unroll
;                     for (int r = 0; r < 4; ++r) {
;                         LAS bf16* up = XU + (16 * rb + 4 * kq + r) * XU_STRIDE + 16 * gi + fr;
;                         const float u = __uint_as_float((unsigned)(*up) << 16);
;                         *up = f2bf(gelu_t(acc[r] + dsk[gi] * u));
;                     }
;                 }
	v_fma_f32 v207, v180, v110, v207
	v_fma_f32 v110, v179, v110, v243
	v_fma_f32 v108, v179, v108, v207
	v_cvt_pk_bf16_f32 v197, v110, v108
	ds_write_b32 v107, v197 offset:10320
	v_fma_f32 v244, -v180, v108, v244
	v_fma_f32 v208, v180, v110, v208
	v_fma_f32 v110, v179, v110, v244
	v_fma_f32 v108, v179, v108, v208
	v_cvt_pk_bf16_f32 v197, v110, v108
	ds_write_b32 v107, v197 offset:10592
	v_fma_f32 v245, -v180, v108, v245
	v_fma_f32 v209, v180, v110, v209
	v_fma_f32 v110, v179, v110, v245
	v_fma_f32 v108, v179, v108, v209
	v_cvt_pk_bf16_f32 v197, v110, v108
	ds_write_b32 v107, v197 offset:10864
	v_fma_f32 v12, -v180, v108, v12
	v_fma_f32 v226, v180, v110, v226
	v_fma_f32 v110, v179, v110, v12
	v_fma_f32 v108, v179, v108, v226
	v_cvt_pk_bf16_f32 v197, v110, v108
	ds_write_b32 v107, v197 offset:11136
	v_fma_f32 v13, -v180, v108, v13
	v_fma_f32 v227, v180, v110, v227
	v_fma_f32 v110, v179, v110, v13
	v_fma_f32 v108, v179, v108, v227
	v_cvt_pk_bf16_f32 v197, v110, v108
	ds_write_b32 v107, v197 offset:11408
	v_fma_f32 v14, -v180, v108, v14
	v_fma_f32 v228, v180, v110, v228
	v_fma_f32 v110, v179, v110, v14
	v_fma_f32 v108, v179, v108, v228
	v_cvt_pk_bf16_f32 v197, v110, v108
	ds_write_b32 v107, v197 offset:11680
	v_fma_f32 v15, -v180, v108, v15
	v_fma_f32 v229, v180, v110, v229
	v_fma_f32 v110, v179, v110, v15
	v_fma_f32 v108, v179, v108, v229
	v_cvt_pk_bf16_f32 v197, v110, v108
	ds_write_b32 v107, v197 offset:11952
	v_fma_f32 v246, -v180, v108, v246
	v_fma_f32 v210, v180, v110, v210
	v_fma_f32 v110, v179, v110, v246
	v_fma_f32 v108, v179, v108, v210
	v_cvt_pk_bf16_f32 v197, v110, v108
	ds_write_b32 v107, v197 offset:12224
	v_fma_f32 v247, -v180, v108, v247
	v_fma_f32 v211, v180, v110, v211
	v_fma_f32 v110, v179, v110, v247
	v_fma_f32 v108, v179, v108, v211
	v_cvt_pk_bf16_f32 v197, v110, v108
	ds_write_b32 v107, v197 offset:12496
	v_fma_f32 v248, -v180, v108, v248
	v_fma_f32 v212, v180, v110, v212
	v_fma_f32 v110, v179, v110, v248
	v_fma_f32 v108, v179, v108, v212
	v_cvt_pk_bf16_f32 v197, v110, v108
	ds_write_b32 v107, v197 offset:12768
	v_fma_f32 v249, -v180, v108, v249
	v_fma_f32 v213, v180, v110, v213
	v_fma_f32 v110, v179, v110, v249
	v_fma_f32 v108, v179, v108, v213
	v_cvt_pk_bf16_f32 v197, v110, v108
	ds_write_b32 v107, v197 offset:13040
	s_waitcnt lgkmcnt(0)
	ds_read_b128 v[214:217], v194 offset:4608
	ds_read_b128 v[218:221], v194 offset:4672
	ds_read_b128 v[222:225], v194 offset:4736
	ds_read_b128 v[226:229], v194 offset:4800
	ds_read_b128 v[234:237], v194 offset:8960
	ds_read_b128 v[238:241], v194 offset:9024
	ds_read_b128 v[242:245], v194 offset:9088
	ds_read_b128 v[246:249], v194 offset:9152
	ds_read_u16 v8, v195 offset:64
	ds_read_u16 v9, v195 offset:208
	ds_read_u16 v10, v195 offset:352
	ds_read_u16 v11, v195 offset:496
	ds_read_u16 v12, v195 offset:2368
	ds_read_u16 v13, v195 offset:2512
	ds_read_u16 v14, v195 offset:2656
	ds_read_u16 v15, v195 offset:2800
	s_waitcnt vmcnt(8) lgkmcnt(8)
	v_mfma_f32_16x16x32_bf16 v[0:3], v[214:217], v[44:47], 0
	v_mfma_f32_16x16x32_bf16 v[4:7], v[234:237], v[44:47], 0
	v_mfma_f32_16x16x32_bf16 v[0:3], v[218:221], v[40:43], v[0:3]
	v_mfma_f32_16x16x32_bf16 v[4:7], v[238:241], v[40:43], v[4:7]
	v_mfma_f32_16x16x32_bf16 v[0:3], v[222:225], v[32:35], v[0:3]
	v_mfma_f32_16x16x32_bf16 v[4:7], v[242:245], v[32:35], v[4:7]
	v_mfma_f32_16x16x32_bf16 v[0:3], v[226:229], v[36:39], v[0:3]
	v_mfma_f32_16x16x32_bf16 v[4:7], v[246:249], v[36:39], v[4:7]
	s_waitcnt lgkmcnt(0)
	v_lshlrev_b32_e32 v8, 16, v8
	v_lshlrev_b32_e32 v9, 16, v9
	v_lshlrev_b32_e32 v10, 16, v10
	v_lshlrev_b32_e32 v11, 16, v11
	v_lshlrev_b32_e32 v12, 16, v12
	v_lshlrev_b32_e32 v13, 16, v13
	v_lshlrev_b32_e32 v14, 16, v14
	v_lshlrev_b32_e32 v15, 16, v15
	v_fma_f32 v0, v181, v8, v0
	v_fma_f32 v1, v181, v9, v1
	v_fma_f32 v2, v181, v10, v2
	v_fma_f32 v3, v181, v11, v3
	v_fma_f32 v4, v181, v12, v4
	v_fma_f32 v5, v181, v13, v5
	v_fma_f32 v6, v181, v14, v6
	v_fma_f32 v7, v181, v15, v7
	v_mul_f32_e32 v198, 0x3d372713, v0
	v_mul_f32_e32 v199, 0x3d372713, v1
	v_mul_f32_e32 v200, 0x3d372713, v2
	v_mul_f32_e32 v201, 0x3d372713, v3
	v_mul_f32_e32 v202, 0x3d372713, v4
	v_mul_f32_e32 v203, 0x3d372713, v5
	v_mul_f32_e32 v204, 0x3d372713, v6
	v_mul_f32_e32 v205, 0x3d372713, v7
	v_mul_f32_e32 v198, v0, v198
	v_mul_f32_e32 v199, v1, v199
	v_mul_f32_e32 v200, v2, v200
	v_mul_f32_e32 v201, v3, v201
	v_mul_f32_e32 v202, v4, v202
	v_mul_f32_e32 v203, v5, v203
	v_mul_f32_e32 v204, v6, v204
	v_mul_f32_e32 v205, v7, v205
	v_fma_f32 v198, v0, v198, v0
	v_fma_f32 v199, v1, v199, v1
	v_fma_f32 v200, v2, v200, v2
	v_fma_f32 v201, v3, v201, v3
	v_fma_f32 v202, v4, v202, v4
	v_fma_f32 v203, v5, v203, v5
	v_fma_f32 v204, v6, v204, v6
	v_fma_f32 v205, v7, v205, v7
	v_mul_f32_e32 v198, 0x3fcc422a, v198
	v_mul_f32_e32 v199, 0x3fcc422a, v199
	v_mul_f32_e32 v200, 0x3fcc422a, v200
	v_mul_f32_e32 v201, 0x3fcc422a, v201
	v_mul_f32_e32 v202, 0x3fcc422a, v202
	v_mul_f32_e32 v203, 0x3fcc422a, v203
	v_mul_f32_e32 v204, 0x3fcc422a, v204
	v_mul_f32_e32 v205, 0x3fcc422a, v205
	v_mul_f32_e32 v198, 0xbfb8aa3b, v198
	v_mul_f32_e32 v199, 0xbfb8aa3b, v199
	v_mul_f32_e32 v200, 0xbfb8aa3b, v200
	v_mul_f32_e32 v201, 0xbfb8aa3b, v201
	v_mul_f32_e32 v202, 0xbfb8aa3b, v202
	v_mul_f32_e32 v203, 0xbfb8aa3b, v203
	v_mul_f32_e32 v204, 0xbfb8aa3b, v204
	v_mul_f32_e32 v205, 0xbfb8aa3b, v205
	v_exp_f32_e32 v198, v198
	v_exp_f32_e32 v199, v199
	v_exp_f32_e32 v200, v200
	v_exp_f32_e32 v201, v201
	v_exp_f32_e32 v202, v202
	v_exp_f32_e32 v203, v203
	v_exp_f32_e32 v204, v204
	v_exp_f32_e32 v205, v205
	v_add_f32_e32 v198, 1.0, v198
	v_add_f32_e32 v199, 1.0, v199
	v_add_f32_e32 v200, 1.0, v200
	v_add_f32_e32 v201, 1.0, v201
	v_add_f32_e32 v202, 1.0, v202
	v_add_f32_e32 v203, 1.0, v203
	v_add_f32_e32 v204, 1.0, v204
	v_add_f32_e32 v205, 1.0, v205
	v_rcp_f32_e32 v198, v198
	v_rcp_f32_e32 v199, v199
	v_rcp_f32_e32 v200, v200
	v_rcp_f32_e32 v201, v201
	v_rcp_f32_e32 v202, v202
	v_rcp_f32_e32 v203, v203
	v_rcp_f32_e32 v204, v204
	v_rcp_f32_e32 v205, v205
	v_mul_f32_e32 v0, v0, v198
	v_mul_f32_e32 v1, v1, v199
	v_mul_f32_e32 v2, v2, v200
	v_mul_f32_e32 v3, v3, v201
	v_mul_f32_e32 v4, v4, v202
	v_mul_f32_e32 v5, v5, v203
	v_mul_f32_e32 v6, v6, v204
	v_mul_f32_e32 v7, v7, v205
	v_cvt_pk_bf16_f32 v0, v0, v101
	v_cvt_pk_bf16_f32 v1, v1, v101
	v_cvt_pk_bf16_f32 v2, v2, v101
	v_cvt_pk_bf16_f32 v3, v3, v101
	v_cvt_pk_bf16_f32 v4, v4, v101
	v_cvt_pk_bf16_f32 v5, v5, v101
	v_cvt_pk_bf16_f32 v6, v6, v101
	v_cvt_pk_bf16_f32 v7, v7, v101
	ds_write_b16 v195, v0 offset:64
	ds_write_b16 v195, v1 offset:208
	ds_write_b16 v195, v2 offset:352
	ds_write_b16 v195, v3 offset:496
	ds_write_b16 v195, v4 offset:2368
	ds_write_b16 v195, v5 offset:2512
	ds_write_b16 v195, v6 offset:2656
	ds_write_b16 v195, v7 offset:2800
	s_waitcnt lgkmcnt(0)
; #define LAS __attribute__((address_space(3)))
; template <bool PASS2>
; __device__ __forceinline__ void s5_tile(const Ctx& C, int T, int sb_lo, int sb_hi, LAS unsigned char* lds, int wave, int lane) {
;     ...
;         for (int gi = 0; gi < 4; ++gi) {
;             const int g = wave * 4 + gi, gnx = wave * 4 + ((gi + 1) & 3);
;             bfx8 bb[4], cm[4];
; #pragma unroll
;             for (int cb = 0; cb < 4; ++cb) { bb[cb] = bbn[cb]; bbn[cb] = *(const bfx8*)(BBt + ((size_t)(gnx * 128 + cb * 32 + tl)) * GN + 8 * hh); }
;             if (PASS2) {
; #pragma unroll
;                 for (int ks = 0; ks < 4; ++ks) { cm[ks] = cmn[ks]; cmn[ks] = *(const bfx8*)(CMt + ((size_t)(gnx * GN + fr)) * 128 + 32 * ks + 8 * kq); }
;             }
;             float s0ar = 0.f, s0ai = 0.f, s0br = 0.f, s0bi = 0.f;
;             if (sample) { const size_t o0 = ((size_t)(2 * sb) * NG + g) * NP + lane, o1 = o0 + (size_t)NG * NP;
;                 s0ar = C.in(2)[o0]; s0ai = C.in(3)[o0]; s0br = C.in(2)[o1]; s0bi = C.in(3)[o1]; }
;             const bfx8 a = *(const LAS bfx8*)(XU + tl * XU_STRIDE + 16 * gi + 8 * hh);
; #pragma unroll
;             for (int cb = 0; cb < 4; ++cb) {
;                 v16f acc;
; #pragma unroll
;                 for (int r = 0; r < 16; ++r) acc[r] = 0.f;
;                 acc = __builtin_amdgcn_mfma_f32_32x32x16_bf16(bb[cb], a, acc, 0, 0, 0);
; #pragma unroll
;                 for (int rg = 0; rg < 4; ++rg) { v2u w; w.x = cvt_pk_c(acc[4 * rg], acc[4 * rg + 1]); w.y = cvt_pk_c(acc[4 * rg + 2], acc[4 * rg + 3]);
;                     *(LAS v2u*)(BH + tl * BH_STRIDE + cb * 32 + 8 * rg + 4 * hh) = w; }
;             }
;             LDS_FENCE();
;             {
;                 unsigned bu[32];
; #pragma unroll
;                 for (int t = 0; t < 32; ++t) bu[t] = *(const LAS unsigned*)(BH + t * BH_STRIDE + 2 * lane);
;                 LDS_FENCE();
;                 float xr = sr[gi], xi = si[gi];
; #pragma unroll
;                 for (int t = 0; t < 32; ++t) {
;                     if (sample && t == 0) { xr = s0ar; xi = s0ai; }
;                     if (sample && t == 16) { xr = s0br; xi = s0bi; }
;                     const float nr = fmaf(lr[gi], xr, fmaf(-li[gi], xi, bf_lo(bu[t]))), ni = fmaf(lr[gi], xi, fmaf(li[gi], xr, bf_hi(bu[t])));
;                     xr = nr; xi = ni;
;                     if (PASS2) {
	global_load_dwordx4 v[76:79], v[124:125], off
	global_load_dwordx4 v[72:75], v[122:123], off
	global_load_dwordx4 v[68:71], v[120:121], off
	global_load_dwordx4 v[64:67], v[118:119], off
	ds_read_b128 v[250:253], v192 offset:96
	s_waitcnt vmcnt(11) lgkmcnt(0)
	v_mfma_f32_32x32x16_bf16 v[0:15], v[250:253], v[92:95], 0
	global_load_dwordx4 v[44:47], v[156:157], off
	global_load_dwordx4 v[40:43], v[156:157], off offset:64
	global_load_dwordx4 v[36:39], v[156:157], off offset:128
	global_load_dwordx4 v[32:35], v[156:157], off offset:192
	s_waitcnt vmcnt(14)
	v_mfma_f32_32x32x16_bf16 v[214:229], v[250:253], v[88:91], 0
	s_waitcnt vmcnt(13)
	v_mfma_f32_32x32x16_bf16 v[234:249], v[250:253], v[84:87], 0
	s_waitcnt vmcnt(12)
	v_mfma_f32_32x32x16_bf16 v[198:213], v[250:253], v[80:83], 0
	s_nop 11
	v_permlane32_swap_b32_e32 v0, v234
	v_permlane32_swap_b32_e32 v1, v235
	v_permlane32_swap_b32_e32 v2, v236
	v_permlane32_swap_b32_e32 v3, v237
	v_permlane32_swap_b32_e32 v4, v238
	v_permlane32_swap_b32_e32 v5, v239
	v_permlane32_swap_b32_e32 v6, v240
	v_permlane32_swap_b32_e32 v7, v241
	v_permlane32_swap_b32_e32 v8, v242
	v_permlane32_swap_b32_e32 v9, v243
	v_permlane32_swap_b32_e32 v10, v244
	v_permlane32_swap_b32_e32 v11, v245
	v_permlane32_swap_b32_e32 v12, v246
	v_permlane32_swap_b32_e32 v13, v247
	v_permlane32_swap_b32_e32 v14, v248
	v_permlane32_swap_b32_e32 v15, v249
	v_permlane32_swap_b32_e32 v214, v198
	v_permlane32_swap_b32_e32 v215, v199
	v_permlane32_swap_b32_e32 v216, v200
	v_permlane32_swap_b32_e32 v217, v201
	v_permlane32_swap_b32_e32 v218, v202
	v_permlane32_swap_b32_e32 v219, v203
	v_permlane32_swap_b32_e32 v220, v204
	v_permlane32_swap_b32_e32 v221, v205
	v_permlane32_swap_b32_e32 v222, v206
	v_permlane32_swap_b32_e32 v223, v207
	v_permlane32_swap_b32_e32 v224, v208
	v_permlane32_swap_b32_e32 v225, v209
	v_permlane32_swap_b32_e32 v226, v210
	v_permlane32_swap_b32_e32 v227, v211
	v_permlane32_swap_b32_e32 v228, v212
	v_permlane32_swap_b32_e32 v229, v213
	v_fma_f32 v0, -v190, v109, v0
	v_fma_f32 v214, v190, v111, v214
	v_fma_f32 v111, v189, v111, v0
	v_fma_f32 v109, v189, v109, v214
	v_cvt_pk_bf16_f32 v197, v111, v109
	ds_write_b32 v107, v197 offset:4608
	v_fma_f32 v1, -v190, v109, v1
	v_fma_f32 v215, v190, v111, v215
	v_fma_f32 v111, v189, v111, v1
	v_fma_f32 v109, v189, v109, v215
	v_cvt_pk_bf16_f32 v197, v111, v109
	ds_write_b32 v107, v197 offset:4880
	v_fma_f32 v2, -v190, v109, v2
	v_fma_f32 v216, v190, v111, v216
	v_fma_f32 v111, v189, v111, v2
	v_fma_f32 v109, v189, v109, v216
	v_cvt_pk_bf16_f32 v197, v111, v109
	ds_write_b32 v107, v197 offset:5152
	v_fma_f32 v3, -v190, v109, v3
	v_fma_f32 v217, v190, v111, v217
	v_fma_f32 v111, v189, v111, v3
	v_fma_f32 v109, v189, v109, v217
	v_cvt_pk_bf16_f32 v197, v111, v109
	ds_write_b32 v107, v197 offset:5424
	v_fma_f32 v234, -v190, v109, v234
	v_fma_f32 v198, v190, v111, v198
	v_fma_f32 v111, v189, v111, v234
	v_fma_f32 v109, v189, v109, v198
	v_cvt_pk_bf16_f32 v197, v111, v109
	ds_write_b32 v107, v197 offset:5696
	v_fma_f32 v235, -v190, v109, v235
	v_fma_f32 v199, v190, v111, v199
	v_fma_f32 v111, v189, v111, v235
	v_fma_f32 v109, v189, v109, v199
	v_cvt_pk_bf16_f32 v197, v111, v109
	ds_write_b32 v107, v197 offset:5968
	v_fma_f32 v236, -v190, v109, v236
	v_fma_f32 v200, v190, v111, v200
	v_fma_f32 v111, v189, v111, v236
	v_fma_f32 v109, v189, v109, v200
	v_cvt_pk_bf16_f32 v197, v111, v109
	ds_write_b32 v107, v197 offset:6240
	v_fma_f32 v237, -v190, v109, v237
	v_fma_f32 v201, v190, v111, v201
	v_fma_f32 v111, v189, v111, v237
	v_fma_f32 v109, v189, v109, v201
	v_cvt_pk_bf16_f32 v197, v111, v109
	ds_write_b32 v107, v197 offset:6512
	v_fma_f32 v4, -v190, v109, v4
	v_fma_f32 v218, v190, v111, v218
	v_fma_f32 v111, v189, v111, v4
	v_fma_f32 v109, v189, v109, v218
	v_cvt_pk_bf16_f32 v197, v111, v109
	ds_write_b32 v107, v197 offset:6784
	v_fma_f32 v5, -v190, v109, v5
	v_fma_f32 v219, v190, v111, v219
	v_fma_f32 v111, v189, v111, v5
	v_fma_f32 v109, v189, v109, v219
	v_cvt_pk_bf16_f32 v197, v111, v109
	ds_write_b32 v107, v197 offset:7056
	v_fma_f32 v6, -v190, v109, v6
	v_fma_f32 v220, v190, v111, v220
	v_fma_f32 v111, v189, v111, v6
	v_fma_f32 v109, v189, v109, v220
	v_cvt_pk_bf16_f32 v197, v111, v109
	ds_write_b32 v107, v197 offset:7328
	v_fma_f32 v7, -v190, v109, v7
	v_fma_f32 v221, v190, v111, v221
	v_fma_f32 v111, v189, v111, v7
	v_fma_f32 v109, v189, v109, v221
	v_cvt_pk_bf16_f32 v197, v111, v109
	ds_write_b32 v107, v197 offset:7600
	v_fma_f32 v238, -v190, v109, v238
	v_fma_f32 v202, v190, v111, v202
	v_fma_f32 v111, v189, v111, v238
	v_fma_f32 v109, v189, v109, v202
	v_cvt_pk_bf16_f32 v197, v111, v109
	ds_write_b32 v107, v197 offset:7872
	v_fma_f32 v239, -v190, v109, v239
	v_fma_f32 v203, v190, v111, v203
	v_fma_f32 v111, v189, v111, v239
	v_fma_f32 v109, v189, v109, v203
	v_cvt_pk_bf16_f32 v197, v111, v109
	ds_write_b32 v107, v197 offset:8144
	v_fma_f32 v240, -v190, v109, v240
	v_fma_f32 v204, v190, v111, v204
	v_fma_f32 v111, v189, v111, v240
	v_fma_f32 v109, v189, v109, v204
	v_cvt_pk_bf16_f32 v197, v111, v109
	ds_write_b32 v107, v197 offset:8416
	v_fma_f32 v241, -v190, v109, v241
	v_fma_f32 v205, v190, v111, v205
	v_fma_f32 v111, v189, v111, v241
	v_fma_f32 v109, v189, v109, v205
	v_cvt_pk_bf16_f32 v197, v111, v109
	ds_write_b32 v107, v197 offset:8688
	v_fma_f32 v8, -v190, v109, v8
	v_fma_f32 v222, v190, v111, v222
	v_fma_f32 v111, v189, v111, v8
	v_fma_f32 v109, v189, v109, v222
	v_cvt_pk_bf16_f32 v197, v111, v109
	ds_write_b32 v107, v197 offset:8960
	v_fma_f32 v9, -v190, v109, v9
	v_fma_f32 v223, v190, v111, v223
	v_fma_f32 v111, v189, v111, v9
	v_fma_f32 v109, v189, v109, v223
; __device__ __forceinline__ float bf_lo(unsigned w) { return __uint_as_float(w << 16); }
; __device__ __forceinline__ float bf_hi(unsigned w) { return __uint_as_float(w & 0xffff0000u); }
; __device__ __forceinline__ float gelu_t(float x) { const float u = 1.5957691216057308f * (x + 0.044715f * x * x * x); return x * sigmoid_f(u); }
; #define LAS __attribute__((address_space(3)))
; #define LDS_FENCE() asm volatile("s_waitcnt lgkmcnt(0)" ::: "memory")
; template <bool PASS2>
; __device__ __forceinline__ void s5_tile(const Ctx& C, int T, int sb_lo, int sb_hi, LAS unsigned char* lds, int wave, int lane) {
;     ...
;                 float xr = sr[gi], xi = si[gi];
; #pragma unroll
;                 for (int t = 0; t < 32; ++t) {
;                     if (sample && t == 0) { xr = s0ar; xi = s0ai; }
;                     if (sample && t == 16) { xr = s0br; xi = s0bi; }
;                     const float nr = fmaf(lr[gi], xr, fmaf(-li[gi], xi, bf_lo(bu[t]))), ni = fmaf(lr[gi], xi, fmaf(li[gi], xr, bf_hi(bu[t])));
;                     xr = nr; xi = ni;
;                     if (PASS2) {
;                         *(LAS unsigned*)(BH + t * BH_STRIDE + 2 * lane) = cvt_pk_nv(xr, xi);
;                         if (sample && (t & 15) == 15) { const int seq = 2 * sb + (t >> 4);
;                             C.out()[OFF_SRE_S + ((size_t)seq * NG + g) * NP + lane] = xr; C.out()[OFF_SIM_S + ((size_t)seq * NG + g) * NP + lane] = xi; }
;                     }
;                 }
;                 sr[gi] = xr; si[gi] = xi;
;             }
;             LDS_FENCE();
;             if (PASS2) {
; #pragma unroll
;                 for (int rb = 0; rb < 2; ++rb) {
;                     v4f acc = (v4f){0.f, 0.f, 0.f, 0.f};
; #pragma unroll
;                     for (int ks = 0; ks < 4; ++ks) {
;                         const bfx8 sa = *(const LAS bfx8*)(BH + (16 * rb + fr) * BH_STRIDE + 32 * ks + 8 * kq);
;                         acc = __builtin_amdgcn_mfma_f32_16x16x32_bf16(sa, cm[ks], acc, 0, 0, 0);
;                     }
; #pragma unroll
;                     for (int r = 0; r < 4; ++r) {
;                         LAS bf16* up = XU + (16 * rb + 4 * kq + r) * XU_STRIDE + 16 * gi + fr;
;                         const float u = __uint_as_float((unsigned)(*up) << 16);
;                         *up = f2bf(gelu_t(acc[r] + dsk[gi] * u));
;                     }
;                 }
	v_cvt_pk_bf16_f32 v197, v111, v109
	ds_write_b32 v107, v197 offset:9232
	v_fma_f32 v10, -v190, v109, v10
	v_fma_f32 v224, v190, v111, v224
	v_fma_f32 v111, v189, v111, v10
	v_fma_f32 v109, v189, v109, v224
	v_cvt_pk_bf16_f32 v197, v111, v109
	ds_write_b32 v107, v197 offset:9504
	v_fma_f32 v11, -v190, v109, v11
	v_fma_f32 v225, v190, v111, v225
	v_fma_f32 v111, v189, v111, v11
	v_fma_f32 v109, v189, v109, v225
	v_cvt_pk_bf16_f32 v197, v111, v109
	ds_write_b32 v107, v197 offset:9776
	v_fma_f32 v242, -v190, v109, v242
	v_fma_f32 v206, v190, v111, v206
	v_fma_f32 v111, v189, v111, v242
	v_fma_f32 v109, v189, v109, v206
	v_cvt_pk_bf16_f32 v197, v111, v109
	ds_write_b32 v107, v197 offset:10048
	v_fma_f32 v243, -v190, v109, v243
	v_fma_f32 v207, v190, v111, v207
	v_fma_f32 v111, v189, v111, v243
	v_fma_f32 v109, v189, v109, v207
	v_cvt_pk_bf16_f32 v197, v111, v109
	ds_write_b32 v107, v197 offset:10320
	v_fma_f32 v244, -v190, v109, v244
	v_fma_f32 v208, v190, v111, v208
	v_fma_f32 v111, v189, v111, v244
	v_fma_f32 v109, v189, v109, v208
	v_cvt_pk_bf16_f32 v197, v111, v109
	ds_write_b32 v107, v197 offset:10592
	v_fma_f32 v245, -v190, v109, v245
	v_fma_f32 v209, v190, v111, v209
	v_fma_f32 v111, v189, v111, v245
	v_fma_f32 v109, v189, v109, v209
	v_cvt_pk_bf16_f32 v197, v111, v109
	ds_write_b32 v107, v197 offset:10864
	v_fma_f32 v12, -v190, v109, v12
	v_fma_f32 v226, v190, v111, v226
	v_fma_f32 v111, v189, v111, v12
	v_fma_f32 v109, v189, v109, v226
	v_cvt_pk_bf16_f32 v197, v111, v109
	ds_write_b32 v107, v197 offset:11136
	v_fma_f32 v13, -v190, v109, v13
	v_fma_f32 v227, v190, v111, v227
	v_fma_f32 v111, v189, v111, v13
	v_fma_f32 v109, v189, v109, v227
	v_cvt_pk_bf16_f32 v197, v111, v109
	ds_write_b32 v107, v197 offset:11408
	v_fma_f32 v14, -v190, v109, v14
	v_fma_f32 v228, v190, v111, v228
	v_fma_f32 v111, v189, v111, v14
	v_fma_f32 v109, v189, v109, v228
	v_cvt_pk_bf16_f32 v197, v111, v109
	ds_write_b32 v107, v197 offset:11680
	v_fma_f32 v15, -v190, v109, v15
	v_fma_f32 v229, v190, v111, v229
	v_fma_f32 v111, v189, v111, v15
	v_fma_f32 v109, v189, v109, v229
	v_cvt_pk_bf16_f32 v197, v111, v109
	ds_write_b32 v107, v197 offset:11952
	v_fma_f32 v246, -v190, v109, v246
	v_fma_f32 v210, v190, v111, v210
	v_fma_f32 v111, v189, v111, v246
	v_fma_f32 v109, v189, v109, v210
	v_cvt_pk_bf16_f32 v197, v111, v109
	ds_write_b32 v107, v197 offset:12224
	v_fma_f32 v247, -v190, v109, v247
	v_fma_f32 v211, v190, v111, v211
	v_fma_f32 v111, v189, v111, v247
	v_fma_f32 v109, v189, v109, v211
	v_cvt_pk_bf16_f32 v197, v111, v109
	ds_write_b32 v107, v197 offset:12496
	v_fma_f32 v248, -v190, v109, v248
	v_fma_f32 v212, v190, v111, v212
	v_fma_f32 v111, v189, v111, v248
	v_fma_f32 v109, v189, v109, v212
	v_cvt_pk_bf16_f32 v197, v111, v109
	ds_write_b32 v107, v197 offset:12768
	v_fma_f32 v249, -v190, v109, v249
	v_fma_f32 v213, v190, v111, v213
	v_fma_f32 v111, v189, v111, v249
	v_fma_f32 v109, v189, v109, v213
	v_cvt_pk_bf16_f32 v197, v111, v109
	ds_write_b32 v107, v197 offset:13040
	s_waitcnt lgkmcnt(0)
	ds_read_b128 v[214:217], v194 offset:4608
	ds_read_b128 v[218:221], v194 offset:4672
	ds_read_b128 v[222:225], v194 offset:4736
	ds_read_b128 v[226:229], v194 offset:4800
	ds_read_b128 v[234:237], v194 offset:8960
	ds_read_b128 v[238:241], v194 offset:9024
	ds_read_b128 v[242:245], v194 offset:9088
	ds_read_b128 v[246:249], v194 offset:9152
	ds_read_u16 v8, v195 offset:96
	ds_read_u16 v9, v195 offset:240
	ds_read_u16 v10, v195 offset:384
	ds_read_u16 v11, v195 offset:528
	ds_read_u16 v12, v195 offset:2400
	ds_read_u16 v13, v195 offset:2544
	ds_read_u16 v14, v195 offset:2688
	ds_read_u16 v15, v195 offset:2832
	s_waitcnt vmcnt(8) lgkmcnt(8)
	v_mfma_f32_16x16x32_bf16 v[0:3], v[214:217], v[60:63], 0
	v_mfma_f32_16x16x32_bf16 v[4:7], v[234:237], v[60:63], 0
	v_mfma_f32_16x16x32_bf16 v[0:3], v[218:221], v[56:59], v[0:3]
	v_mfma_f32_16x16x32_bf16 v[4:7], v[238:241], v[56:59], v[4:7]
	v_mfma_f32_16x16x32_bf16 v[0:3], v[222:225], v[48:51], v[0:3]
	v_mfma_f32_16x16x32_bf16 v[4:7], v[242:245], v[48:51], v[4:7]
	v_mfma_f32_16x16x32_bf16 v[0:3], v[226:229], v[52:55], v[0:3]
	v_mfma_f32_16x16x32_bf16 v[4:7], v[246:249], v[52:55], v[4:7]
	s_waitcnt lgkmcnt(0)
; __device__ __forceinline__ float gelu_t(float x) { const float u = 1.5957691216057308f * (x + 0.044715f * x * x * x); return x * sigmoid_f(u); }
; #define LAS __attribute__((address_space(3)))
; #define LDS_FENCE() asm volatile("s_waitcnt lgkmcnt(0)" ::: "memory")
; __device__ __forceinline__ bf16 f2bf(float f) { return (bf16)(cvt_pk_nv(f, 0.f) & 0xffffu); }
; template <bool PASS2>
; __device__ __forceinline__ void s5_tile(const Ctx& C, int T, int sb_lo, int sb_hi, LAS unsigned char* lds, int wave, int lane) {
;     ...
;                     for (int r = 0; r < 4; ++r) {
;                         LAS bf16* up = XU + (16 * rb + 4 * kq + r) * XU_STRIDE + 16 * gi + fr;
;                         const float u = __uint_as_float((unsigned)(*up) << 16);
;                         *up = f2bf(gelu_t(acc[r] + dsk[gi] * u));
;                     }
;                 }
;                 LDS_FENCE();
;             }
;         }
;         if (PASS2) {
; #pragma unroll
;             for (int i = 0; i < 4; ++i) *(v4u*)(C.YB() + (size_t)(rb0 + xrow + 8 * i) * BWD + 64 * wave + 8 * xpart) = *(const LAS v4u*)(XU + (xrow + 8 * i) * XU_STRIDE + 8 * xpart);
;             LDS_FENCE();
	v_lshlrev_b32_e32 v8, 16, v8
	v_lshlrev_b32_e32 v9, 16, v9
	v_lshlrev_b32_e32 v10, 16, v10
	v_lshlrev_b32_e32 v11, 16, v11
	v_lshlrev_b32_e32 v12, 16, v12
	v_lshlrev_b32_e32 v13, 16, v13
	v_lshlrev_b32_e32 v14, 16, v14
	v_lshlrev_b32_e32 v15, 16, v15
	v_fma_f32 v0, v191, v8, v0
	v_fma_f32 v1, v191, v9, v1
	v_fma_f32 v2, v191, v10, v2
	v_fma_f32 v3, v191, v11, v3
	v_fma_f32 v4, v191, v12, v4
	v_fma_f32 v5, v191, v13, v5
	v_fma_f32 v6, v191, v14, v6
	v_fma_f32 v7, v191, v15, v7
	v_mul_f32_e32 v198, 0x3d372713, v0
	v_mul_f32_e32 v199, 0x3d372713, v1
	v_mul_f32_e32 v200, 0x3d372713, v2
	v_mul_f32_e32 v201, 0x3d372713, v3
	v_mul_f32_e32 v202, 0x3d372713, v4
	v_mul_f32_e32 v203, 0x3d372713, v5
	v_mul_f32_e32 v204, 0x3d372713, v6
	v_mul_f32_e32 v205, 0x3d372713, v7
	v_mul_f32_e32 v198, v0, v198
	v_mul_f32_e32 v199, v1, v199
	v_mul_f32_e32 v200, v2, v200
	v_mul_f32_e32 v201, v3, v201
	v_mul_f32_e32 v202, v4, v202
	v_mul_f32_e32 v203, v5, v203
	v_mul_f32_e32 v204, v6, v204
	v_mul_f32_e32 v205, v7, v205
	v_fma_f32 v198, v0, v198, v0
	v_fma_f32 v199, v1, v199, v1
	v_fma_f32 v200, v2, v200, v2
	v_fma_f32 v201, v3, v201, v3
	v_fma_f32 v202, v4, v202, v4
	v_fma_f32 v203, v5, v203, v5
	v_fma_f32 v204, v6, v204, v6
	v_fma_f32 v205, v7, v205, v7
	v_mul_f32_e32 v198, 0x3fcc422a, v198
	v_mul_f32_e32 v199, 0x3fcc422a, v199
	v_mul_f32_e32 v200, 0x3fcc422a, v200
	v_mul_f32_e32 v201, 0x3fcc422a, v201
	v_mul_f32_e32 v202, 0x3fcc422a, v202
	v_mul_f32_e32 v203, 0x3fcc422a, v203
	v_mul_f32_e32 v204, 0x3fcc422a, v204
	v_mul_f32_e32 v205, 0x3fcc422a, v205
	v_mul_f32_e32 v198, 0xbfb8aa3b, v198
	v_mul_f32_e32 v199, 0xbfb8aa3b, v199
	v_mul_f32_e32 v200, 0xbfb8aa3b, v200
	v_mul_f32_e32 v201, 0xbfb8aa3b, v201
	v_mul_f32_e32 v202, 0xbfb8aa3b, v202
	v_mul_f32_e32 v203, 0xbfb8aa3b, v203
	v_mul_f32_e32 v204, 0xbfb8aa3b, v204
	v_mul_f32_e32 v205, 0xbfb8aa3b, v205
	v_exp_f32_e32 v198, v198
	v_exp_f32_e32 v199, v199
	v_exp_f32_e32 v200, v200
	v_exp_f32_e32 v201, v201
	v_exp_f32_e32 v202, v202
	v_exp_f32_e32 v203, v203
	v_exp_f32_e32 v204, v204
	v_exp_f32_e32 v205, v205
	v_add_f32_e32 v198, 1.0, v198
	v_add_f32_e32 v199, 1.0, v199
	v_add_f32_e32 v200, 1.0, v200
	v_add_f32_e32 v201, 1.0, v201
	v_add_f32_e32 v202, 1.0, v202
	v_add_f32_e32 v203, 1.0, v203
	v_add_f32_e32 v204, 1.0, v204
	v_add_f32_e32 v205, 1.0, v205
	v_rcp_f32_e32 v198, v198
	v_rcp_f32_e32 v199, v199
	v_rcp_f32_e32 v200, v200
	v_rcp_f32_e32 v201, v201
	v_rcp_f32_e32 v202, v202
	v_rcp_f32_e32 v203, v203
	v_rcp_f32_e32 v204, v204
	v_rcp_f32_e32 v205, v205
	v_mul_f32_e32 v0, v0, v198
	v_mul_f32_e32 v1, v1, v199
	v_mul_f32_e32 v2, v2, v200
	v_mul_f32_e32 v3, v3, v201
	v_mul_f32_e32 v4, v4, v202
	v_mul_f32_e32 v5, v5, v203
	v_mul_f32_e32 v6, v6, v204
	v_mul_f32_e32 v7, v7, v205
	v_cvt_pk_bf16_f32 v0, v0, v101
	v_cvt_pk_bf16_f32 v1, v1, v101
	v_cvt_pk_bf16_f32 v2, v2, v101
	v_cvt_pk_bf16_f32 v3, v3, v101
	v_cvt_pk_bf16_f32 v4, v4, v101
	v_cvt_pk_bf16_f32 v5, v5, v101
	v_cvt_pk_bf16_f32 v6, v6, v101
	v_cvt_pk_bf16_f32 v7, v7, v101
	ds_write_b16 v195, v0 offset:96
	ds_write_b16 v195, v1 offset:240
	ds_write_b16 v195, v2 offset:384
	ds_write_b16 v195, v3 offset:528
	ds_write_b16 v195, v4 offset:2400
	ds_write_b16 v195, v5 offset:2544
	ds_write_b16 v195, v6 offset:2688
	ds_write_b16 v195, v7 offset:2832
	v_ashrrev_i32_e32 v159, 31, v158
	v_lshlrev_b64 v[4:5], 10, v[158:159]
	s_waitcnt lgkmcnt(0)
	ds_read_b128 v[0:3], v196
	s_load_dwordx2 s[0:1], s[0:1], 0x110
	s_waitcnt lgkmcnt(0)
	v_lshl_add_u64 v[4:5], s[0:1], 0, v[4:5]
	v_lshl_add_u64 v[4:5], v[4:5], 0, s[10:11]
	v_lshl_add_u64 v[4:5], v[4:5], 0, v[100:101]
	v_add_co_u32_e32 v4, vcc, s47, v4
	s_mov_b64 s[0:1], s[80:81]
	s_nop 0
	v_addc_co_u32_e32 v5, vcc, 0, v5, vcc
	global_store_dwordx4 v[4:5], v[0:3], off
	ds_read_b128 v[0:3], v196 offset:1152
	s_load_dwordx2 s[0:1], s[0:1], 0x110
	v_add_u32_e32 v4, 8, v158
	v_ashrrev_i32_e32 v5, 31, v4
	v_lshlrev_b64 v[4:5], 10, v[4:5]
	s_waitcnt lgkmcnt(0)
	v_lshl_add_u64 v[4:5], s[0:1], 0, v[4:5]
	v_lshl_add_u64 v[4:5], v[4:5], 0, s[10:11]
	v_lshl_add_u64 v[4:5], v[4:5], 0, v[100:101]
	v_add_co_u32_e32 v4, vcc, s47, v4
	s_mov_b64 s[0:1], s[80:81]
	s_nop 0
	v_addc_co_u32_e32 v5, vcc, 0, v5, vcc
	global_store_dwordx4 v[4:5], v[0:3], off
	ds_read_b128 v[0:3], v196 offset:2304
	s_load_dwordx2 s[0:1], s[0:1], 0x110
	v_add_u32_e32 v4, 16, v158
	v_ashrrev_i32_e32 v5, 31, v4
	v_lshlrev_b64 v[4:5], 10, v[4:5]
	s_waitcnt lgkmcnt(0)
	v_lshl_add_u64 v[4:5], s[0:1], 0, v[4:5]
	v_lshl_add_u64 v[4:5], v[4:5], 0, s[10:11]
	v_lshl_add_u64 v[4:5], v[4:5], 0, v[100:101]
	v_add_co_u32_e32 v4, vcc, s47, v4
	s_mov_b64 s[0:1], s[80:81]
	s_nop 0
	v_addc_co_u32_e32 v5, vcc, 0, v5, vcc
	global_store_dwordx4 v[4:5], v[0:3], off
	ds_read_b128 v[0:3], v196 offset:3456
	s_load_dwordx2 s[0:1], s[0:1], 0x110
	v_add_u32_e32 v4, 24, v158
	v_ashrrev_i32_e32 v5, 31, v4
	v_lshlrev_b64 v[4:5], 10, v[4:5]
	s_waitcnt lgkmcnt(0)
	v_lshl_add_u64 v[4:5], s[0:1], 0, v[4:5]
	v_lshl_add_u64 v[4:5], v[4:5], 0, s[10:11]
	v_lshl_add_u64 v[4:5], v[4:5], 0, v[100:101]
	v_add_co_u32_e32 v4, vcc, 0x11300000, v4
	s_nop 1
	v_addc_co_u32_e32 v5, vcc, 0, v5, vcc
	global_store_dwordx4 v[4:5], v[0:3], off
	s_waitcnt lgkmcnt(0)
	s_cbranch_scc1 .LBB0_671

; #define FTID const int ftid_ = fresh_tid()
; #define WAVE (__builtin_amdgcn_readfirstlane(ftid_ >> 6))
; __global__ void __launch_bounds__(NTHREADS, 2) fwd_kernel(Args args) {
;     ...
;     { FTID; const bool swap0 = GSZ > 128;
;       for (int T = BX; T < NTILE - 1; T += GSZ) { if (swap0 && T == 0) continue; s5_tile<true>(C, T, 0, 4, lds, WAVE, LANE); }
;       if (swap0 && BX == 128) s5_tile<true>(C, 0, 0, 4, lds, WAVE, LANE);
;       if (BX >= 1 && BX <= 4) s5_tile<true>(C, NTILE - 1, BX - 1, BX, lds, WAVE, LANE);
.LBB0_673:
	s_cmpk_eq_i32 s33, 0x80
	s_cselect_b64 s[0:1], -1, 0
	s_and_b64 s[0:1], s[0:1], s[52:53]
	s_and_b64 vcc, exec, s[0:1]
	s_cbranch_vccz .Lmy_p6_no_t0
	s_cmp_lg_u32 s98, 0
	s_cbranch_scc1 .Lmy_p6_no_t0
	s_mov_b32 s98, 1
	s_mov_b32 s77, 0
	s_mov_b32 s76, 0
	v_mov_b32_e32 v172, v162
	s_branch .Lmy_p6_tile_entry
.Lmy_p6_no_t0:
	v_lshlrev_b32_e32 v144, 4, v160
	v_readlane_b32 s77, v232, 7

; __global__ void __launch_bounds__(NTHREADS, 2) fwd_kernel(Args args) {
	.amdhsa_kernel _Z10fwd_kernel4Args
		.amdhsa_group_segment_fixed_size 0
		.amdhsa_private_segment_fixed_size 0
		.amdhsa_kernarg_size 536
		.amdhsa_user_sgpr_count 2
		.amdhsa_user_sgpr_dispatch_ptr 0
		.amdhsa_user_sgpr_queue_ptr 0
		.amdhsa_user_sgpr_kernarg_segment_ptr 1
		.amdhsa_user_sgpr_dispatch_id 0
		.amdhsa_user_sgpr_kernarg_preload_length 0
		.amdhsa_user_sgpr_kernarg_preload_offset 0
		.amdhsa_user_sgpr_private_segment_size 0
		.amdhsa_uses_dynamic_stack 0
		.amdhsa_enable_private_segment 0
		.amdhsa_system_sgpr_workgroup_id_x 1
		.amdhsa_system_sgpr_workgroup_id_y 0
		.amdhsa_system_sgpr_workgroup_id_z 0
		.amdhsa_system_sgpr_workgroup_info 0
		.amdhsa_system_vgpr_workitem_id 2
		.amdhsa_next_free_vgpr 256
		.amdhsa_next_free_sgpr 99
		.amdhsa_accum_offset 256
		.amdhsa_reserve_vcc 1
		.amdhsa_float_round_mode_32 0
		.amdhsa_float_round_mode_16_64 0
		.amdhsa_float_denorm_mode_32 3
		.amdhsa_float_denorm_mode_16_64 3
		.amdhsa_dx10_clamp 1
		.amdhsa_ieee_mode 1
		.amdhsa_fp16_overflow 0
		.amdhsa_tg_split 0
		.amdhsa_exception_fp_ieee_invalid_op 0
		.amdhsa_exception_fp_denorm_src 0
		.amdhsa_exception_fp_ieee_div_zero 0
		.amdhsa_exception_fp_ieee_overflow 0
		.amdhsa_exception_fp_ieee_underflow 0
		.amdhsa_exception_fp_ieee_inexact 0
		.amdhsa_exception_int_div_zero 0
	.end_amdhsa_kernel

; __global__ void __launch_bounds__(NTHREADS, 2) fwd_kernel(Args args) {
amdhsa.kernels:
  - .agpr_count:     0
    .args:
      - .offset:         0
        .size:           280
        .value_kind:     by_value
      - .offset:         280
        .size:           4
        .value_kind:     hidden_block_count_x
      - .offset:         284
        .size:           4
        .value_kind:     hidden_block_count_y
      - .offset:         288
        .size:           4
        .value_kind:     hidden_block_count_z
      - .offset:         292
        .size:           2
        .value_kind:     hidden_group_size_x
      - .offset:         294
        .size:           2
        .value_kind:     hidden_group_size_y
      - .offset:         296
        .size:           2
        .value_kind:     hidden_group_size_z
      - .offset:         298
        .size:           2
        .value_kind:     hidden_remainder_x
      - .offset:         300
        .size:           2
        .value_kind:     hidden_remainder_y
      - .offset:         302
        .size:           2
        .value_kind:     hidden_remainder_z
      - .offset:         320
        .size:           8
        .value_kind:     hidden_global_offset_x
      - .offset:         328
        .size:           8
        .value_kind:     hidden_global_offset_y
      - .offset:         336
        .size:           8
        .value_kind:     hidden_global_offset_z
      - .offset:         344
        .size:           2
        .value_kind:     hidden_grid_dims
      - .offset:         368
        .size:           8
        .value_kind:     hidden_multigrid_sync_arg
      - .offset:         400
        .size:           4
        .value_kind:     hidden_dynamic_lds_size
    .group_segment_fixed_size: 0
    .kernarg_segment_align: 8
    .kernarg_segment_size: 536
    .language:       OpenCL C
    .language_version:
      - 2
      - 0
    .max_flat_workgroup_size: 512
    .name:           _Z10fwd_kernel4Args
    .private_segment_fixed_size: 0
    .sgpr_count:     105
    .sgpr_spill_count: 11
    .symbol:         _Z10fwd_kernel4Args.kd
    .uniform_work_group_size: 1
    .uses_dynamic_stack: false
    .vgpr_count:     256
    .vgpr_spill_count: 0
    .wavefront_size: 64
